# in-proj: LDS-DMA issue interleaved with MFMAs, B tile double-buffered, epilogue bases formed late
# speedup vs baseline: 1.1194x; 1.0016x over previous
.Lip_entry:
	v_and_b32_e32 v225, 63, v170
	v_lshrrev_b32_e32 v226, 6, v170
	v_lshrrev_b32_e32 v227, 1, v226
	v_and_b32_e32 v228, 1, v226
	v_and_b32_e32 v229, 15, v225
	v_lshrrev_b32_e32 v230, 4, v225
	v_lshlrev_b32_e32 v231, 10, v226
	v_lshrrev_b32_e32 v232, 3, v170
	v_readfirstlane_b32 s52, v231
	v_and_b32_e32 v233, 7, v170
	v_bfe_u32 v224, v232, 1, 3
	v_xor_b32_e32 v233, v233, v224
	v_lshlrev_b32_e32 v233, 4, v233
	s_movk_i32 s4, 0x880
	v_mad_u32_u24 v224, v232, s4, v233
	v_and_b32_e32 v233, 15, v232
	v_lshlrev_b32_e32 v233, 1, v233
	v_lshrrev_b32_e32 v168, 4, v232
	v_add_u32_e32 v233, v233, v168
	v_and_b32_e32 v168, 7, v170
	v_bfe_u32 v169, v232, 1, 3
	v_xor_b32_e32 v168, v168, v169
	v_lshlrev_b32_e32 v168, 4, v168
	v_mad_u32_u24 v168, v233, s4, v168
	v_bfe_u32 v233, v229, 1, 3
	v_xor_b32_e32 v231, v230, v233
	v_or_b32_e32 v232, 4, v230
	v_xor_b32_e32 v232, v232, v233
	v_lshlrev_b32_e32 v231, 4, v231
	v_lshlrev_b32_e32 v232, 4, v232
	v_lshl_add_u32 v233, v227, 7, v229
	v_lshlrev_b32_e32 v233, 7, v233
	v_add_u32_e32 v220, v233, v231
	v_add_u32_e32 v221, v233, v232
	v_lshl_add_u32 v233, v228, 6, v229
	v_lshlrev_b32_e32 v233, 7, v233
	v_add_u32_e32 v233, 0x8000, v233
	v_add_u32_e32 v222, v233, v231
	v_add_u32_e32 v223, v233, v232
	v_lshlrev_b32_e32 v231, 7, v227
	v_lshl_add_u32 v231, v230, 2, v231
	v_lshlrev_b32_e32 v232, 5, v228
	v_add_u32_e32 v232, v232, v229
	v_lshlrev_b32_e32 v232, 1, v232
	s_movk_i32 s4, 0x3600
	v_lshlrev_b32_e32 v233, 2, v232
	v_mad_u32_u24 v225, v231, s4, v233
	s_movk_i32 s4, 0x300
	v_lshlrev_b32_e32 v233, 1, v232
	v_mad_u32_u24 v169, v231, s4, v233
	v_readlane_b32 s54, v237, 0
	s_cmp_ge_u32 s54, 1296
	s_cbranch_scc1 .Lip_done
	s_add_u32 s57, s52, 0x8000
	s_lshr_b32 s55, s54, 4
	s_mul_hi_u32 s55, s55, 0x55555556
	s_mul_i32 s53, s55, 48
	s_sub_u32 s53, s54, s53
	v_readlane_b32 s4, v235, 34
	v_readlane_b32 s5, v235, 35
	s_mul_i32 s34, s53, 0x88000
	s_add_u32 s34, s34, 0xe166000
	s_add_u32 s34, s34, s4
	s_addc_u32 s35, s5, 0
	s_mul_i32 s36, s55, 0x44000
	s_add_u32 s36, s36, s40
	s_addc_u32 s37, s41, 0
	s_lshr_b32 s55, s54, 4
	s_mul_hi_u32 s55, s55, 0x55555556
	s_mul_i32 s53, s55, 48
	s_sub_u32 s53, s54, s53
	v_readlane_b32 s4, v235, 34
	v_readlane_b32 s5, v235, 35
	s_lshl_b32 s56, s53, 8
	s_or_b32 s56, s56, s55
	s_add_u32 m0, s52, 0x0
	s_add_u32 s4, s34, 0x0
	s_addc_u32 s5, s35, 0
	global_load_lds_dwordx4 v224, s[4:5]
	s_add_u32 m0, s52, 0x1000
	s_add_u32 s4, s34, 0x11000
	s_addc_u32 s5, s35, 0
	global_load_lds_dwordx4 v224, s[4:5]
	s_add_u32 m0, s52, 0x2000
	s_add_u32 s4, s34, 0x22000
	s_addc_u32 s5, s35, 0
	global_load_lds_dwordx4 v224, s[4:5]
	s_add_u32 m0, s52, 0x3000
	s_add_u32 s4, s34, 0x33000
	s_addc_u32 s5, s35, 0
	global_load_lds_dwordx4 v224, s[4:5]
	s_add_u32 m0, s52, 0x4000
	s_add_u32 s4, s34, 0x44000
	s_addc_u32 s5, s35, 0
	global_load_lds_dwordx4 v224, s[4:5]
	s_add_u32 m0, s52, 0x5000
	s_add_u32 s4, s34, 0x55000
	s_addc_u32 s5, s35, 0
	global_load_lds_dwordx4 v224, s[4:5]
	s_add_u32 m0, s52, 0x6000
	s_add_u32 s4, s34, 0x66000
	s_addc_u32 s5, s35, 0
	global_load_lds_dwordx4 v224, s[4:5]
	s_add_u32 m0, s52, 0x7000
	s_add_u32 s4, s34, 0x77000
	s_addc_u32 s5, s35, 0
	global_load_lds_dwordx4 v224, s[4:5]
	s_add_u32 m0, s52, 0x8000
	s_add_u32 s4, s36, 0x0
	s_addc_u32 s5, s37, 0
	global_load_lds_dwordx4 v168, s[4:5]
	s_add_u32 m0, s52, 0x9000
	s_add_u32 s4, s36, 0x11000
	s_addc_u32 s5, s37, 0
	global_load_lds_dwordx4 v168, s[4:5]
	s_add_u32 m0, s52, 0xa000
	s_add_u32 s4, s36, 0x22000
	s_addc_u32 s5, s37, 0
	global_load_lds_dwordx4 v168, s[4:5]
	s_add_u32 m0, s52, 0xb000
	s_add_u32 s4, s36, 0x33000
	s_addc_u32 s5, s37, 0
	global_load_lds_dwordx4 v168, s[4:5]
	s_add_u32 s34, s34, 0x80
	s_addc_u32 s35, s35, 0
	s_add_u32 s36, s36, 0x80
	s_addc_u32 s37, s37, 0

.Lip_k:
	s_waitcnt vmcnt(0)
	s_barrier
	s_cmp_eq_u32 s53, 15
	s_cbranch_scc1 .Lip_nob
	s_xor_b32 s57, s57, 0x4000
	s_add_u32 m0, s57, 0x0
	s_add_u32 s4, s36, 0x0
	s_addc_u32 s5, s37, 0
	global_load_lds_dwordx4 v168, s[4:5]
	s_add_u32 m0, s57, 0x1000
	s_add_u32 s4, s36, 0x11000
	s_addc_u32 s5, s37, 0
	global_load_lds_dwordx4 v168, s[4:5]
	s_add_u32 m0, s57, 0x2000
	s_add_u32 s4, s36, 0x22000
	s_addc_u32 s5, s37, 0
	global_load_lds_dwordx4 v168, s[4:5]
	s_add_u32 m0, s57, 0x3000
	s_add_u32 s4, s36, 0x33000
	s_addc_u32 s5, s37, 0
	global_load_lds_dwordx4 v168, s[4:5]
	s_add_u32 s36, s36, 0x80
	s_addc_u32 s37, s37, 0
	s_branch .Lip_nob2

.Lip_nob2:
	ds_read_b128 v[204:207], v222
	ds_read_b128 v[208:211], v222 offset:2048
	ds_read_b128 v[212:215], v222 offset:4096
	ds_read_b128 v[216:219], v222 offset:6144
	ds_read_b128 a[0:3], v223
	ds_read_b128 a[4:7], v223 offset:2048
	ds_read_b128 a[8:11], v223 offset:4096
	ds_read_b128 a[12:15], v223 offset:6144
	ds_read_b128 v[136:139], v220
	ds_read_b128 v[140:143], v220 offset:2048
	ds_read_b128 v[144:147], v220 offset:4096
	ds_read_b128 v[148:151], v220 offset:6144
	ds_read_b128 v[152:155], v220 offset:8192
	ds_read_b128 v[156:159], v220 offset:10240
	ds_read_b128 v[160:163], v220 offset:12288
	ds_read_b128 v[164:167], v220 offset:14336
	s_waitcnt lgkmcnt(7)
	v_mfma_f32_16x16x32_bf16 v[0:3], v[136:139], v[204:207], v[0:3]
	v_mfma_f32_16x16x32_bf16 v[4:7], v[136:139], v[208:211], v[4:7]
	v_mfma_f32_16x16x32_bf16 v[8:11], v[136:139], v[212:215], v[8:11]
	v_mfma_f32_16x16x32_bf16 v[12:15], v[136:139], v[216:219], v[12:15]
	ds_read_b128 v[136:139], v221
	s_waitcnt lgkmcnt(7)
	v_mfma_f32_16x16x32_bf16 v[16:19], v[140:143], v[204:207], v[16:19]
	v_mfma_f32_16x16x32_bf16 v[20:23], v[140:143], v[208:211], v[20:23]
	v_mfma_f32_16x16x32_bf16 v[24:27], v[140:143], v[212:215], v[24:27]
	v_mfma_f32_16x16x32_bf16 v[28:31], v[140:143], v[216:219], v[28:31]
	ds_read_b128 v[140:143], v221 offset:2048
	s_waitcnt lgkmcnt(7)
	v_mfma_f32_16x16x32_bf16 v[32:35], v[144:147], v[204:207], v[32:35]
	v_mfma_f32_16x16x32_bf16 v[36:39], v[144:147], v[208:211], v[36:39]
	v_mfma_f32_16x16x32_bf16 v[40:43], v[144:147], v[212:215], v[40:43]
	v_mfma_f32_16x16x32_bf16 v[44:47], v[144:147], v[216:219], v[44:47]
	ds_read_b128 v[144:147], v221 offset:4096
	s_waitcnt lgkmcnt(7)
	v_mfma_f32_16x16x32_bf16 v[48:51], v[148:151], v[204:207], v[48:51]
	v_mfma_f32_16x16x32_bf16 v[52:55], v[148:151], v[208:211], v[52:55]
	v_mfma_f32_16x16x32_bf16 v[56:59], v[148:151], v[212:215], v[56:59]
	v_mfma_f32_16x16x32_bf16 v[60:63], v[148:151], v[216:219], v[60:63]
	ds_read_b128 v[148:151], v221 offset:6144
	s_waitcnt lgkmcnt(7)
	v_mfma_f32_16x16x32_bf16 v[64:67], v[152:155], v[204:207], v[64:67]
	v_mfma_f32_16x16x32_bf16 v[68:71], v[152:155], v[208:211], v[68:71]
	v_mfma_f32_16x16x32_bf16 v[72:75], v[152:155], v[212:215], v[72:75]
	v_mfma_f32_16x16x32_bf16 v[76:79], v[152:155], v[216:219], v[76:79]
	ds_read_b128 v[152:155], v221 offset:8192
	s_waitcnt lgkmcnt(7)
	v_mfma_f32_16x16x32_bf16 v[80:83], v[156:159], v[204:207], v[80:83]
	v_mfma_f32_16x16x32_bf16 v[84:87], v[156:159], v[208:211], v[84:87]
	v_mfma_f32_16x16x32_bf16 v[88:91], v[156:159], v[212:215], v[88:91]
	v_mfma_f32_16x16x32_bf16 v[92:95], v[156:159], v[216:219], v[92:95]
	ds_read_b128 v[156:159], v221 offset:10240
	s_waitcnt lgkmcnt(7)
	v_mfma_f32_16x16x32_bf16 v[96:99], v[160:163], v[204:207], v[96:99]
	v_mfma_f32_16x16x32_bf16 v[100:103], v[160:163], v[208:211], v[100:103]
	v_mfma_f32_16x16x32_bf16 v[104:107], v[160:163], v[212:215], v[104:107]
	v_mfma_f32_16x16x32_bf16 v[108:111], v[160:163], v[216:219], v[108:111]
	ds_read_b128 v[160:163], v221 offset:12288
	s_waitcnt lgkmcnt(7)
	v_mfma_f32_16x16x32_bf16 v[112:115], v[164:167], v[204:207], v[112:115]
	v_mfma_f32_16x16x32_bf16 v[116:119], v[164:167], v[208:211], v[116:119]
	v_mfma_f32_16x16x32_bf16 v[120:123], v[164:167], v[212:215], v[120:123]
	v_mfma_f32_16x16x32_bf16 v[124:127], v[164:167], v[216:219], v[124:127]
	ds_read_b128 v[164:167], v221 offset:14336
	s_waitcnt lgkmcnt(0)
	s_barrier
	v_xor_b32_e32 v222, 0x4000, v222
	v_xor_b32_e32 v223, 0x4000, v223
	s_cmp_eq_u32 s53, 15
	s_cbranch_scc1 .Lip_last
	v_mfma_f32_16x16x32_bf16 v[0:3], v[136:139], a[0:3], v[0:3]
	s_add_u32 m0, s52, 0x0
	s_add_u32 s4, s34, 0x0
	s_addc_u32 s5, s35, 0
	global_load_lds_dwordx4 v224, s[4:5]
	v_mfma_f32_16x16x32_bf16 v[4:7], v[136:139], a[4:7], v[4:7]
	v_mfma_f32_16x16x32_bf16 v[8:11], v[136:139], a[8:11], v[8:11]
	s_add_u32 m0, s52, 0x1000
	s_add_u32 s4, s34, 0x11000
	s_addc_u32 s5, s35, 0
	global_load_lds_dwordx4 v224, s[4:5]
	v_mfma_f32_16x16x32_bf16 v[12:15], v[136:139], a[12:15], v[12:15]
	v_mfma_f32_16x16x32_bf16 v[16:19], v[140:143], a[0:3], v[16:19]
	s_add_u32 m0, s52, 0x2000
	s_add_u32 s4, s34, 0x22000
	s_addc_u32 s5, s35, 0
	global_load_lds_dwordx4 v224, s[4:5]
	v_mfma_f32_16x16x32_bf16 v[20:23], v[140:143], a[4:7], v[20:23]
	v_mfma_f32_16x16x32_bf16 v[24:27], v[140:143], a[8:11], v[24:27]
	s_add_u32 m0, s52, 0x3000
	s_add_u32 s4, s34, 0x33000
	s_addc_u32 s5, s35, 0
	global_load_lds_dwordx4 v224, s[4:5]
	v_mfma_f32_16x16x32_bf16 v[28:31], v[140:143], a[12:15], v[28:31]
	v_mfma_f32_16x16x32_bf16 v[32:35], v[144:147], a[0:3], v[32:35]
	s_add_u32 m0, s52, 0x4000
	s_add_u32 s4, s34, 0x44000
	s_addc_u32 s5, s35, 0
	global_load_lds_dwordx4 v224, s[4:5]
	v_mfma_f32_16x16x32_bf16 v[36:39], v[144:147], a[4:7], v[36:39]
	v_mfma_f32_16x16x32_bf16 v[40:43], v[144:147], a[8:11], v[40:43]
	s_add_u32 m0, s52, 0x5000
	s_add_u32 s4, s34, 0x55000
	s_addc_u32 s5, s35, 0
	global_load_lds_dwordx4 v224, s[4:5]
	v_mfma_f32_16x16x32_bf16 v[44:47], v[144:147], a[12:15], v[44:47]
	v_mfma_f32_16x16x32_bf16 v[48:51], v[148:151], a[0:3], v[48:51]
	s_add_u32 m0, s52, 0x6000
	s_add_u32 s4, s34, 0x66000
	s_addc_u32 s5, s35, 0
	global_load_lds_dwordx4 v224, s[4:5]
	v_mfma_f32_16x16x32_bf16 v[52:55], v[148:151], a[4:7], v[52:55]
	v_mfma_f32_16x16x32_bf16 v[56:59], v[148:151], a[8:11], v[56:59]
	s_add_u32 m0, s52, 0x7000
	s_add_u32 s4, s34, 0x77000
	s_addc_u32 s5, s35, 0
	global_load_lds_dwordx4 v224, s[4:5]
	v_mfma_f32_16x16x32_bf16 v[60:63], v[148:151], a[12:15], v[60:63]
	v_mfma_f32_16x16x32_bf16 v[64:67], v[152:155], a[0:3], v[64:67]
	v_mfma_f32_16x16x32_bf16 v[68:71], v[152:155], a[4:7], v[68:71]
	v_mfma_f32_16x16x32_bf16 v[72:75], v[152:155], a[8:11], v[72:75]
	v_mfma_f32_16x16x32_bf16 v[76:79], v[152:155], a[12:15], v[76:79]
	v_mfma_f32_16x16x32_bf16 v[80:83], v[156:159], a[0:3], v[80:83]
	v_mfma_f32_16x16x32_bf16 v[84:87], v[156:159], a[4:7], v[84:87]
	v_mfma_f32_16x16x32_bf16 v[88:91], v[156:159], a[8:11], v[88:91]
	v_mfma_f32_16x16x32_bf16 v[92:95], v[156:159], a[12:15], v[92:95]
	v_mfma_f32_16x16x32_bf16 v[96:99], v[160:163], a[0:3], v[96:99]
	v_mfma_f32_16x16x32_bf16 v[100:103], v[160:163], a[4:7], v[100:103]
	v_mfma_f32_16x16x32_bf16 v[104:107], v[160:163], a[8:11], v[104:107]
	v_mfma_f32_16x16x32_bf16 v[108:111], v[160:163], a[12:15], v[108:111]
	v_mfma_f32_16x16x32_bf16 v[112:115], v[164:167], a[0:3], v[112:115]
	v_mfma_f32_16x16x32_bf16 v[116:119], v[164:167], a[4:7], v[116:119]
	v_mfma_f32_16x16x32_bf16 v[120:123], v[164:167], a[8:11], v[120:123]
	v_mfma_f32_16x16x32_bf16 v[124:127], v[164:167], a[12:15], v[124:127]
	s_add_u32 s34, s34, 0x80
	s_addc_u32 s35, s35, 0
	s_add_u32 s53, s53, 1
	s_branch .Lip_k

.Lip_nopf:
	v_mfma_f32_16x16x32_bf16 v[0:3], v[136:139], a[0:3], v[0:3]
	v_mfma_f32_16x16x32_bf16 v[4:7], v[136:139], a[4:7], v[4:7]
	v_mfma_f32_16x16x32_bf16 v[8:11], v[136:139], a[8:11], v[8:11]
	v_mfma_f32_16x16x32_bf16 v[12:15], v[136:139], a[12:15], v[12:15]
	v_mfma_f32_16x16x32_bf16 v[16:19], v[140:143], a[0:3], v[16:19]
	v_mfma_f32_16x16x32_bf16 v[20:23], v[140:143], a[4:7], v[20:23]
	v_mfma_f32_16x16x32_bf16 v[24:27], v[140:143], a[8:11], v[24:27]
	v_mfma_f32_16x16x32_bf16 v[28:31], v[140:143], a[12:15], v[28:31]
	v_mfma_f32_16x16x32_bf16 v[32:35], v[144:147], a[0:3], v[32:35]
	v_mfma_f32_16x16x32_bf16 v[36:39], v[144:147], a[4:7], v[36:39]
	v_mfma_f32_16x16x32_bf16 v[40:43], v[144:147], a[8:11], v[40:43]
	v_mfma_f32_16x16x32_bf16 v[44:47], v[144:147], a[12:15], v[44:47]
	v_mfma_f32_16x16x32_bf16 v[48:51], v[148:151], a[0:3], v[48:51]
	v_mfma_f32_16x16x32_bf16 v[52:55], v[148:151], a[4:7], v[52:55]
	v_mfma_f32_16x16x32_bf16 v[56:59], v[148:151], a[8:11], v[56:59]
	v_mfma_f32_16x16x32_bf16 v[60:63], v[148:151], a[12:15], v[60:63]
	v_mfma_f32_16x16x32_bf16 v[64:67], v[152:155], a[0:3], v[64:67]
	v_mfma_f32_16x16x32_bf16 v[68:71], v[152:155], a[4:7], v[68:71]
	v_mfma_f32_16x16x32_bf16 v[72:75], v[152:155], a[8:11], v[72:75]
	v_mfma_f32_16x16x32_bf16 v[76:79], v[152:155], a[12:15], v[76:79]
	v_mfma_f32_16x16x32_bf16 v[80:83], v[156:159], a[0:3], v[80:83]
	v_mfma_f32_16x16x32_bf16 v[84:87], v[156:159], a[4:7], v[84:87]
	v_mfma_f32_16x16x32_bf16 v[88:91], v[156:159], a[8:11], v[88:91]
	v_mfma_f32_16x16x32_bf16 v[92:95], v[156:159], a[12:15], v[92:95]
	v_mfma_f32_16x16x32_bf16 v[96:99], v[160:163], a[0:3], v[96:99]
	v_mfma_f32_16x16x32_bf16 v[100:103], v[160:163], a[4:7], v[100:103]
	v_mfma_f32_16x16x32_bf16 v[104:107], v[160:163], a[8:11], v[104:107]
	v_mfma_f32_16x16x32_bf16 v[108:111], v[160:163], a[12:15], v[108:111]
	v_mfma_f32_16x16x32_bf16 v[112:115], v[164:167], a[0:3], v[112:115]
	v_mfma_f32_16x16x32_bf16 v[116:119], v[164:167], a[4:7], v[116:119]
	v_mfma_f32_16x16x32_bf16 v[120:123], v[164:167], a[8:11], v[120:123]
	v_mfma_f32_16x16x32_bf16 v[124:127], v[164:167], a[12:15], v[124:127]
	s_nop 7
	s_nop 7
	s_and_b32 s55, s56, 0xff
	s_lshr_b32 s53, s56, 8
	v_readlane_b32 s4, v235, 34
	v_readlane_b32 s5, v235, 35
	s_mul_i32 s46, s53, 0x360000
	s_lshl_b32 s50, s55, 9
	s_add_u32 s46, s46, s50
	s_add_u32 s46, s46, 0xfae6000
	s_add_u32 s46, s46, s4
	s_addc_u32 s47, s5, 0
	s_mul_i32 s50, s53, 0x30000
	s_lshl_b32 s51, s55, 8
	s_add_u32 s50, s50, s51
	s_add_u32 s50, s50, 0x19ce5a00
	s_add_u32 s50, s50, s4
	s_addc_u32 s51, s5, 0
	v_mov_b32_e32 v226, s46
	v_mov_b32_e32 v227, s47
	v_add_co_u32_e32 v226, vcc, v226, v225
	s_nop 1
	v_addc_co_u32_e32 v227, vcc, 0, v227, vcc
	v_mov_b32_e32 v228, v0
	v_mov_b32_e32 v229, v4
	v_mov_b32_e32 v230, v8
	v_mov_b32_e32 v231, v12
	global_store_dwordx2 v[226:227], v[228:229], off
	global_store_dwordx2 v[226:227], v[230:231], off offset:128
	s_mov_b64 s[4:5], 0x3600
	v_lshl_add_u64 v[226:227], v[226:227], 0, s[4:5]
	v_mov_b32_e32 v228, v1
	v_mov_b32_e32 v229, v5
	v_mov_b32_e32 v230, v9
	v_mov_b32_e32 v231, v13
	global_store_dwordx2 v[226:227], v[228:229], off
	global_store_dwordx2 v[226:227], v[230:231], off offset:128
	s_mov_b64 s[4:5], 0x3600
	v_lshl_add_u64 v[226:227], v[226:227], 0, s[4:5]
	v_mov_b32_e32 v228, v2
	v_mov_b32_e32 v229, v6
	v_mov_b32_e32 v230, v10
	v_mov_b32_e32 v231, v14
	global_store_dwordx2 v[226:227], v[228:229], off
	global_store_dwordx2 v[226:227], v[230:231], off offset:128
	s_mov_b64 s[4:5], 0x3600
	v_lshl_add_u64 v[226:227], v[226:227], 0, s[4:5]
	v_mov_b32_e32 v228, v3
	v_mov_b32_e32 v229, v7
	v_mov_b32_e32 v230, v11
	v_mov_b32_e32 v231, v15
	global_store_dwordx2 v[226:227], v[228:229], off
	global_store_dwordx2 v[226:227], v[230:231], off offset:128
	s_mov_b64 s[4:5], 0x2be00
	v_lshl_add_u64 v[226:227], v[226:227], 0, s[4:5]
	v_mov_b32_e32 v228, v16
	v_mov_b32_e32 v229, v20
	v_mov_b32_e32 v230, v24
	v_mov_b32_e32 v231, v28
	global_store_dwordx2 v[226:227], v[228:229], off
	global_store_dwordx2 v[226:227], v[230:231], off offset:128
	s_mov_b64 s[4:5], 0x3600
	v_lshl_add_u64 v[226:227], v[226:227], 0, s[4:5]
	v_mov_b32_e32 v228, v17
	v_mov_b32_e32 v229, v21
	v_mov_b32_e32 v230, v25
	v_mov_b32_e32 v231, v29
	global_store_dwordx2 v[226:227], v[228:229], off
	global_store_dwordx2 v[226:227], v[230:231], off offset:128
	s_mov_b64 s[4:5], 0x3600
	v_lshl_add_u64 v[226:227], v[226:227], 0, s[4:5]
	v_mov_b32_e32 v228, v18
	v_mov_b32_e32 v229, v22
	v_mov_b32_e32 v230, v26
	v_mov_b32_e32 v231, v30
	global_store_dwordx2 v[226:227], v[228:229], off
	global_store_dwordx2 v[226:227], v[230:231], off offset:128
	s_mov_b64 s[4:5], 0x3600
	v_lshl_add_u64 v[226:227], v[226:227], 0, s[4:5]
	v_mov_b32_e32 v228, v19
	v_mov_b32_e32 v229, v23
	v_mov_b32_e32 v230, v27
	v_mov_b32_e32 v231, v31
	global_store_dwordx2 v[226:227], v[228:229], off
	global_store_dwordx2 v[226:227], v[230:231], off offset:128
	s_mov_b64 s[4:5], 0x2be00
	v_lshl_add_u64 v[226:227], v[226:227], 0, s[4:5]
	v_mov_b32_e32 v228, v32
	v_mov_b32_e32 v229, v36
	v_mov_b32_e32 v230, v40
	v_mov_b32_e32 v231, v44
	global_store_dwordx2 v[226:227], v[228:229], off
	global_store_dwordx2 v[226:227], v[230:231], off offset:128
	s_mov_b64 s[4:5], 0x3600
	v_lshl_add_u64 v[226:227], v[226:227], 0, s[4:5]
	v_mov_b32_e32 v228, v33
	v_mov_b32_e32 v229, v37
	v_mov_b32_e32 v230, v41
	v_mov_b32_e32 v231, v45
	global_store_dwordx2 v[226:227], v[228:229], off
	global_store_dwordx2 v[226:227], v[230:231], off offset:128
	s_mov_b64 s[4:5], 0x3600
	v_lshl_add_u64 v[226:227], v[226:227], 0, s[4:5]
	v_mov_b32_e32 v228, v34
	v_mov_b32_e32 v229, v38
	v_mov_b32_e32 v230, v42
	v_mov_b32_e32 v231, v46
	global_store_dwordx2 v[226:227], v[228:229], off
	global_store_dwordx2 v[226:227], v[230:231], off offset:128
	s_mov_b64 s[4:5], 0x3600
	v_lshl_add_u64 v[226:227], v[226:227], 0, s[4:5]
	v_mov_b32_e32 v228, v35
	v_mov_b32_e32 v229, v39
	v_mov_b32_e32 v230, v43
	v_mov_b32_e32 v231, v47
	global_store_dwordx2 v[226:227], v[228:229], off
	global_store_dwordx2 v[226:227], v[230:231], off offset:128
	s_mov_b64 s[4:5], 0x2be00
	v_lshl_add_u64 v[226:227], v[226:227], 0, s[4:5]
	v_mov_b32_e32 v228, v48
	v_mov_b32_e32 v229, v52
	v_mov_b32_e32 v230, v56
	v_mov_b32_e32 v231, v60
	global_store_dwordx2 v[226:227], v[228:229], off
	global_store_dwordx2 v[226:227], v[230:231], off offset:128
	s_mov_b64 s[4:5], 0x3600
	v_lshl_add_u64 v[226:227], v[226:227], 0, s[4:5]
	v_mov_b32_e32 v228, v49
	v_mov_b32_e32 v229, v53
	v_mov_b32_e32 v230, v57
	v_mov_b32_e32 v231, v61
	global_store_dwordx2 v[226:227], v[228:229], off
	global_store_dwordx2 v[226:227], v[230:231], off offset:128
	s_mov_b64 s[4:5], 0x3600
	v_lshl_add_u64 v[226:227], v[226:227], 0, s[4:5]
	v_mov_b32_e32 v228, v50
	v_mov_b32_e32 v229, v54
	v_mov_b32_e32 v230, v58
	v_mov_b32_e32 v231, v62
	global_store_dwordx2 v[226:227], v[228:229], off
	global_store_dwordx2 v[226:227], v[230:231], off offset:128
	s_mov_b64 s[4:5], 0x3600
	v_lshl_add_u64 v[226:227], v[226:227], 0, s[4:5]
	v_mov_b32_e32 v228, v51
	v_mov_b32_e32 v229, v55
	v_mov_b32_e32 v230, v59
	v_mov_b32_e32 v231, v63
	global_store_dwordx2 v[226:227], v[228:229], off
	global_store_dwordx2 v[226:227], v[230:231], off offset:128
	s_mov_b64 s[4:5], 0x2be00
	v_lshl_add_u64 v[226:227], v[226:227], 0, s[4:5]
	v_mov_b32_e32 v228, v64
	v_mov_b32_e32 v229, v68
	v_mov_b32_e32 v230, v72
	v_mov_b32_e32 v231, v76
	global_store_dwordx2 v[226:227], v[228:229], off
	global_store_dwordx2 v[226:227], v[230:231], off offset:128
	s_mov_b64 s[4:5], 0x3600
	v_lshl_add_u64 v[226:227], v[226:227], 0, s[4:5]
	v_mov_b32_e32 v228, v65
	v_mov_b32_e32 v229, v69
	v_mov_b32_e32 v230, v73
	v_mov_b32_e32 v231, v77
	global_store_dwordx2 v[226:227], v[228:229], off
	global_store_dwordx2 v[226:227], v[230:231], off offset:128
	s_mov_b64 s[4:5], 0x3600
	v_lshl_add_u64 v[226:227], v[226:227], 0, s[4:5]
	v_mov_b32_e32 v228, v66
	v_mov_b32_e32 v229, v70
	v_mov_b32_e32 v230, v74
	v_mov_b32_e32 v231, v78
	global_store_dwordx2 v[226:227], v[228:229], off
	global_store_dwordx2 v[226:227], v[230:231], off offset:128
	s_mov_b64 s[4:5], 0x3600
	v_lshl_add_u64 v[226:227], v[226:227], 0, s[4:5]
	v_mov_b32_e32 v228, v67
	v_mov_b32_e32 v229, v71
	v_mov_b32_e32 v230, v75
	v_mov_b32_e32 v231, v79
	global_store_dwordx2 v[226:227], v[228:229], off
	global_store_dwordx2 v[226:227], v[230:231], off offset:128
	s_mov_b64 s[4:5], 0x2be00
	v_lshl_add_u64 v[226:227], v[226:227], 0, s[4:5]
	v_mov_b32_e32 v228, v80
	v_mov_b32_e32 v229, v84
	v_mov_b32_e32 v230, v88
	v_mov_b32_e32 v231, v92
	global_store_dwordx2 v[226:227], v[228:229], off
	global_store_dwordx2 v[226:227], v[230:231], off offset:128
	s_mov_b64 s[4:5], 0x3600
	v_lshl_add_u64 v[226:227], v[226:227], 0, s[4:5]
	v_mov_b32_e32 v228, v81
	v_mov_b32_e32 v229, v85
	v_mov_b32_e32 v230, v89
	v_mov_b32_e32 v231, v93
	global_store_dwordx2 v[226:227], v[228:229], off
	global_store_dwordx2 v[226:227], v[230:231], off offset:128
	s_mov_b64 s[4:5], 0x3600
	v_lshl_add_u64 v[226:227], v[226:227], 0, s[4:5]
	v_mov_b32_e32 v228, v82
	v_mov_b32_e32 v229, v86
	v_mov_b32_e32 v230, v90
	v_mov_b32_e32 v231, v94
	global_store_dwordx2 v[226:227], v[228:229], off
	global_store_dwordx2 v[226:227], v[230:231], off offset:128
	s_mov_b64 s[4:5], 0x3600
	v_lshl_add_u64 v[226:227], v[226:227], 0, s[4:5]
	v_mov_b32_e32 v228, v83
	v_mov_b32_e32 v229, v87
	v_mov_b32_e32 v230, v91
	v_mov_b32_e32 v231, v95
	global_store_dwordx2 v[226:227], v[228:229], off
	global_store_dwordx2 v[226:227], v[230:231], off offset:128
	s_mov_b64 s[4:5], 0x2be00
	v_lshl_add_u64 v[226:227], v[226:227], 0, s[4:5]
	v_mov_b32_e32 v228, v96
	v_mov_b32_e32 v229, v100
	v_mov_b32_e32 v230, v104
	v_mov_b32_e32 v231, v108
	global_store_dwordx2 v[226:227], v[228:229], off
	global_store_dwordx2 v[226:227], v[230:231], off offset:128
	s_mov_b64 s[4:5], 0x3600
	v_lshl_add_u64 v[226:227], v[226:227], 0, s[4:5]
	v_mov_b32_e32 v228, v97
	v_mov_b32_e32 v229, v101
	v_mov_b32_e32 v230, v105
	v_mov_b32_e32 v231, v109
	global_store_dwordx2 v[226:227], v[228:229], off
	global_store_dwordx2 v[226:227], v[230:231], off offset:128
	s_mov_b64 s[4:5], 0x3600
	v_lshl_add_u64 v[226:227], v[226:227], 0, s[4:5]
	v_mov_b32_e32 v228, v98
	v_mov_b32_e32 v229, v102
	v_mov_b32_e32 v230, v106
	v_mov_b32_e32 v231, v110
	global_store_dwordx2 v[226:227], v[228:229], off
	global_store_dwordx2 v[226:227], v[230:231], off offset:128
	s_mov_b64 s[4:5], 0x3600
	v_lshl_add_u64 v[226:227], v[226:227], 0, s[4:5]
	v_mov_b32_e32 v228, v99
	v_mov_b32_e32 v229, v103
	v_mov_b32_e32 v230, v107
	v_mov_b32_e32 v231, v111
	global_store_dwordx2 v[226:227], v[228:229], off
	global_store_dwordx2 v[226:227], v[230:231], off offset:128
	s_mov_b64 s[4:5], 0x2be00
	v_lshl_add_u64 v[226:227], v[226:227], 0, s[4:5]
	v_mov_b32_e32 v228, v112
	v_mov_b32_e32 v229, v116
	v_mov_b32_e32 v230, v120
	v_mov_b32_e32 v231, v124
	global_store_dwordx2 v[226:227], v[228:229], off
	global_store_dwordx2 v[226:227], v[230:231], off offset:128
	s_mov_b64 s[4:5], 0x3600
	v_lshl_add_u64 v[226:227], v[226:227], 0, s[4:5]
	v_mov_b32_e32 v228, v113
	v_mov_b32_e32 v229, v117
	v_mov_b32_e32 v230, v121
	v_mov_b32_e32 v231, v125
	global_store_dwordx2 v[226:227], v[228:229], off
	global_store_dwordx2 v[226:227], v[230:231], off offset:128
	s_mov_b64 s[4:5], 0x3600
	v_lshl_add_u64 v[226:227], v[226:227], 0, s[4:5]
	v_mov_b32_e32 v228, v114
	v_mov_b32_e32 v229, v118
	v_mov_b32_e32 v230, v122
	v_mov_b32_e32 v231, v126
	global_store_dwordx2 v[226:227], v[228:229], off
	global_store_dwordx2 v[226:227], v[230:231], off offset:128
	s_mov_b64 s[4:5], 0x3600
	v_lshl_add_u64 v[226:227], v[226:227], 0, s[4:5]
	v_mov_b32_e32 v228, v115
	v_mov_b32_e32 v229, v119
	v_mov_b32_e32 v230, v123
	v_mov_b32_e32 v231, v127
	global_store_dwordx2 v[226:227], v[228:229], off
	global_store_dwordx2 v[226:227], v[230:231], off offset:128
	s_and_b32 s55, s56, 0xff
	s_sub_u32 s55, s55, 6
	s_cmp_gt_u32 s55, 2
	s_cbranch_scc1 .Lip_nolin
.Lip_lin0:
	s_cmp_lg_u32 s55, 0
	s_cbranch_scc1 .Lip_lin1
	v_mov_b32_e32 v226, s50
	v_mov_b32_e32 v227, s51
	v_add_co_u32_e32 v226, vcc, v226, v169
	s_nop 1
	v_addc_co_u32_e32 v227, vcc, 0, v227, vcc
	v_add_f32_e32 v228, v0, v0
	v_mul_f32_e32 v228, 0x3fb8aa3b, v228
	v_exp_f32_e32 v228, v228
	s_nop 0
	v_add_f32_e32 v229, 1.0, v228
	v_div_scale_f32 v230, s[4:5], v229, v229, 2.0
	v_rcp_f32_e32 v231, v230
	v_div_scale_f32 v232, vcc, 2.0, v229, 2.0
	v_fma_f32 v131, -v230, v231, 1.0
	v_fmac_f32_e32 v231, v131, v231
	v_mul_f32_e32 v233, v232, v231
	v_fma_f32 v131, -v230, v233, v232
	v_fmac_f32_e32 v233, v131, v231
	v_fma_f32 v230, -v230, v233, v232
	v_div_fmas_f32 v230, v230, v231, v233
	v_div_fixup_f32 v135, v230, v229, 2.0
	v_sub_f32_e32 v135, 1.0, v135
	v_add_f32_e32 v228, v4, v4
	v_mul_f32_e32 v228, 0x3fb8aa3b, v228
	v_exp_f32_e32 v228, v228
	s_nop 0
	v_add_f32_e32 v229, 1.0, v228
	v_div_scale_f32 v230, s[4:5], v229, v229, 2.0
	v_rcp_f32_e32 v231, v230
	v_div_scale_f32 v232, vcc, 2.0, v229, 2.0
	v_fma_f32 v131, -v230, v231, 1.0
	v_fmac_f32_e32 v231, v131, v231
	v_mul_f32_e32 v233, v232, v231
	v_fma_f32 v131, -v230, v233, v232
	v_fmac_f32_e32 v233, v131, v231
	v_fma_f32 v230, -v230, v233, v232
	v_div_fmas_f32 v230, v230, v231, v233
	v_div_fixup_f32 v133, v230, v229, 2.0
	v_sub_f32_e32 v133, 1.0, v133
	v_cvt_pk_bf16_f32 v133, v135, v133
	global_store_dword v[226:227], v133, off
	v_add_f32_e32 v228, v8, v8
	v_mul_f32_e32 v228, 0x3fb8aa3b, v228
	v_exp_f32_e32 v228, v228
	s_nop 0
	v_add_f32_e32 v229, 1.0, v228
	v_div_scale_f32 v230, s[4:5], v229, v229, 2.0
	v_rcp_f32_e32 v231, v230
	v_div_scale_f32 v232, vcc, 2.0, v229, 2.0
	v_fma_f32 v131, -v230, v231, 1.0
	v_fmac_f32_e32 v231, v131, v231
	v_mul_f32_e32 v233, v232, v231
	v_fma_f32 v131, -v230, v233, v232
	v_fmac_f32_e32 v233, v131, v231
	v_fma_f32 v230, -v230, v233, v232
	v_div_fmas_f32 v230, v230, v231, v233
	v_div_fixup_f32 v135, v230, v229, 2.0
	v_sub_f32_e32 v135, 1.0, v135
	v_add_f32_e32 v228, v12, v12
	v_mul_f32_e32 v228, 0x3fb8aa3b, v228
	v_exp_f32_e32 v228, v228
	s_nop 0
	v_add_f32_e32 v229, 1.0, v228
	v_div_scale_f32 v230, s[4:5], v229, v229, 2.0
	v_rcp_f32_e32 v231, v230
	v_div_scale_f32 v232, vcc, 2.0, v229, 2.0
	v_fma_f32 v131, -v230, v231, 1.0
	v_fmac_f32_e32 v231, v131, v231
	v_mul_f32_e32 v233, v232, v231
	v_fma_f32 v131, -v230, v233, v232
	v_fmac_f32_e32 v233, v131, v231
	v_fma_f32 v230, -v230, v233, v232
	v_div_fmas_f32 v230, v230, v231, v233
	v_div_fixup_f32 v133, v230, v229, 2.0
	v_sub_f32_e32 v133, 1.0, v133
	v_cvt_pk_bf16_f32 v133, v135, v133
	global_store_dword v[226:227], v133, off offset:64
	s_mov_b64 s[4:5], 0x300
	v_lshl_add_u64 v[226:227], v[226:227], 0, s[4:5]
	v_add_f32_e32 v228, v1, v1
	v_mul_f32_e32 v228, 0x3fb8aa3b, v228
	v_exp_f32_e32 v228, v228
	s_nop 0
	v_add_f32_e32 v229, 1.0, v228
	v_div_scale_f32 v230, s[4:5], v229, v229, 2.0
	v_rcp_f32_e32 v231, v230
	v_div_scale_f32 v232, vcc, 2.0, v229, 2.0
	v_fma_f32 v131, -v230, v231, 1.0
	v_fmac_f32_e32 v231, v131, v231
	v_mul_f32_e32 v233, v232, v231
	v_fma_f32 v131, -v230, v233, v232
	v_fmac_f32_e32 v233, v131, v231
	v_fma_f32 v230, -v230, v233, v232
	v_div_fmas_f32 v230, v230, v231, v233
	v_div_fixup_f32 v135, v230, v229, 2.0
	v_sub_f32_e32 v135, 1.0, v135
	v_add_f32_e32 v228, v5, v5
	v_mul_f32_e32 v228, 0x3fb8aa3b, v228
	v_exp_f32_e32 v228, v228
	s_nop 0
	v_add_f32_e32 v229, 1.0, v228
	v_div_scale_f32 v230, s[4:5], v229, v229, 2.0
	v_rcp_f32_e32 v231, v230
	v_div_scale_f32 v232, vcc, 2.0, v229, 2.0
	v_fma_f32 v131, -v230, v231, 1.0
	v_fmac_f32_e32 v231, v131, v231
	v_mul_f32_e32 v233, v232, v231
	v_fma_f32 v131, -v230, v233, v232
	v_fmac_f32_e32 v233, v131, v231
	v_fma_f32 v230, -v230, v233, v232
	v_div_fmas_f32 v230, v230, v231, v233
	v_div_fixup_f32 v133, v230, v229, 2.0
	v_sub_f32_e32 v133, 1.0, v133
	v_cvt_pk_bf16_f32 v133, v135, v133
	global_store_dword v[226:227], v133, off
	v_add_f32_e32 v228, v9, v9
	v_mul_f32_e32 v228, 0x3fb8aa3b, v228
	v_exp_f32_e32 v228, v228
	s_nop 0
	v_add_f32_e32 v229, 1.0, v228
	v_div_scale_f32 v230, s[4:5], v229, v229, 2.0
	v_rcp_f32_e32 v231, v230
	v_div_scale_f32 v232, vcc, 2.0, v229, 2.0
	v_fma_f32 v131, -v230, v231, 1.0
	v_fmac_f32_e32 v231, v131, v231
	v_mul_f32_e32 v233, v232, v231
	v_fma_f32 v131, -v230, v233, v232
	v_fmac_f32_e32 v233, v131, v231
	v_fma_f32 v230, -v230, v233, v232
	v_div_fmas_f32 v230, v230, v231, v233
	v_div_fixup_f32 v135, v230, v229, 2.0
	v_sub_f32_e32 v135, 1.0, v135
	v_add_f32_e32 v228, v13, v13
	v_mul_f32_e32 v228, 0x3fb8aa3b, v228
	v_exp_f32_e32 v228, v228
	s_nop 0
	v_add_f32_e32 v229, 1.0, v228
	v_div_scale_f32 v230, s[4:5], v229, v229, 2.0
	v_rcp_f32_e32 v231, v230
	v_div_scale_f32 v232, vcc, 2.0, v229, 2.0
	v_fma_f32 v131, -v230, v231, 1.0
	v_fmac_f32_e32 v231, v131, v231
	v_mul_f32_e32 v233, v232, v231
	v_fma_f32 v131, -v230, v233, v232
	v_fmac_f32_e32 v233, v131, v231
	v_fma_f32 v230, -v230, v233, v232
	v_div_fmas_f32 v230, v230, v231, v233
	v_div_fixup_f32 v133, v230, v229, 2.0
	v_sub_f32_e32 v133, 1.0, v133
	v_cvt_pk_bf16_f32 v133, v135, v133
	global_store_dword v[226:227], v133, off offset:64
	s_mov_b64 s[4:5], 0x300
	v_lshl_add_u64 v[226:227], v[226:227], 0, s[4:5]
	v_add_f32_e32 v228, v2, v2
	v_mul_f32_e32 v228, 0x3fb8aa3b, v228
	v_exp_f32_e32 v228, v228
	s_nop 0
	v_add_f32_e32 v229, 1.0, v228
	v_div_scale_f32 v230, s[4:5], v229, v229, 2.0
	v_rcp_f32_e32 v231, v230
	v_div_scale_f32 v232, vcc, 2.0, v229, 2.0
	v_fma_f32 v131, -v230, v231, 1.0
	v_fmac_f32_e32 v231, v131, v231
	v_mul_f32_e32 v233, v232, v231
	v_fma_f32 v131, -v230, v233, v232
	v_fmac_f32_e32 v233, v131, v231
	v_fma_f32 v230, -v230, v233, v232
	v_div_fmas_f32 v230, v230, v231, v233
	v_div_fixup_f32 v135, v230, v229, 2.0
	v_sub_f32_e32 v135, 1.0, v135
	v_add_f32_e32 v228, v6, v6
	v_mul_f32_e32 v228, 0x3fb8aa3b, v228
	v_exp_f32_e32 v228, v228
	s_nop 0
	v_add_f32_e32 v229, 1.0, v228
	v_div_scale_f32 v230, s[4:5], v229, v229, 2.0
	v_rcp_f32_e32 v231, v230
	v_div_scale_f32 v232, vcc, 2.0, v229, 2.0
	v_fma_f32 v131, -v230, v231, 1.0
	v_fmac_f32_e32 v231, v131, v231
	v_mul_f32_e32 v233, v232, v231
	v_fma_f32 v131, -v230, v233, v232
	v_fmac_f32_e32 v233, v131, v231
	v_fma_f32 v230, -v230, v233, v232
	v_div_fmas_f32 v230, v230, v231, v233
	v_div_fixup_f32 v133, v230, v229, 2.0
	v_sub_f32_e32 v133, 1.0, v133
	v_cvt_pk_bf16_f32 v133, v135, v133
	global_store_dword v[226:227], v133, off
	v_add_f32_e32 v228, v10, v10
	v_mul_f32_e32 v228, 0x3fb8aa3b, v228
	v_exp_f32_e32 v228, v228
	s_nop 0
	v_add_f32_e32 v229, 1.0, v228
	v_div_scale_f32 v230, s[4:5], v229, v229, 2.0
	v_rcp_f32_e32 v231, v230
	v_div_scale_f32 v232, vcc, 2.0, v229, 2.0
	v_fma_f32 v131, -v230, v231, 1.0
	v_fmac_f32_e32 v231, v131, v231
	v_mul_f32_e32 v233, v232, v231
	v_fma_f32 v131, -v230, v233, v232
	v_fmac_f32_e32 v233, v131, v231
	v_fma_f32 v230, -v230, v233, v232
	v_div_fmas_f32 v230, v230, v231, v233
	v_div_fixup_f32 v135, v230, v229, 2.0
	v_sub_f32_e32 v135, 1.0, v135
	v_add_f32_e32 v228, v14, v14
	v_mul_f32_e32 v228, 0x3fb8aa3b, v228
	v_exp_f32_e32 v228, v228
	s_nop 0
	v_add_f32_e32 v229, 1.0, v228
	v_div_scale_f32 v230, s[4:5], v229, v229, 2.0
	v_rcp_f32_e32 v231, v230
	v_div_scale_f32 v232, vcc, 2.0, v229, 2.0
	v_fma_f32 v131, -v230, v231, 1.0
	v_fmac_f32_e32 v231, v131, v231
	v_mul_f32_e32 v233, v232, v231
	v_fma_f32 v131, -v230, v233, v232
	v_fmac_f32_e32 v233, v131, v231
	v_fma_f32 v230, -v230, v233, v232
	v_div_fmas_f32 v230, v230, v231, v233
	v_div_fixup_f32 v133, v230, v229, 2.0
	v_sub_f32_e32 v133, 1.0, v133
	v_cvt_pk_bf16_f32 v133, v135, v133
	global_store_dword v[226:227], v133, off offset:64
	s_mov_b64 s[4:5], 0x300
	v_lshl_add_u64 v[226:227], v[226:227], 0, s[4:5]
	v_add_f32_e32 v228, v3, v3
	v_mul_f32_e32 v228, 0x3fb8aa3b, v228
	v_exp_f32_e32 v228, v228
	s_nop 0
	v_add_f32_e32 v229, 1.0, v228
	v_div_scale_f32 v230, s[4:5], v229, v229, 2.0
	v_rcp_f32_e32 v231, v230
	v_div_scale_f32 v232, vcc, 2.0, v229, 2.0
	v_fma_f32 v131, -v230, v231, 1.0
	v_fmac_f32_e32 v231, v131, v231
	v_mul_f32_e32 v233, v232, v231
	v_fma_f32 v131, -v230, v233, v232
	v_fmac_f32_e32 v233, v131, v231
	v_fma_f32 v230, -v230, v233, v232
	v_div_fmas_f32 v230, v230, v231, v233
	v_div_fixup_f32 v135, v230, v229, 2.0
	v_sub_f32_e32 v135, 1.0, v135
	v_add_f32_e32 v228, v7, v7
	v_mul_f32_e32 v228, 0x3fb8aa3b, v228
	v_exp_f32_e32 v228, v228
	s_nop 0
	v_add_f32_e32 v229, 1.0, v228
	v_div_scale_f32 v230, s[4:5], v229, v229, 2.0
	v_rcp_f32_e32 v231, v230
	v_div_scale_f32 v232, vcc, 2.0, v229, 2.0
	v_fma_f32 v131, -v230, v231, 1.0
	v_fmac_f32_e32 v231, v131, v231
	v_mul_f32_e32 v233, v232, v231
	v_fma_f32 v131, -v230, v233, v232
	v_fmac_f32_e32 v233, v131, v231
	v_fma_f32 v230, -v230, v233, v232
	v_div_fmas_f32 v230, v230, v231, v233
	v_div_fixup_f32 v133, v230, v229, 2.0
	v_sub_f32_e32 v133, 1.0, v133
	v_cvt_pk_bf16_f32 v133, v135, v133
	global_store_dword v[226:227], v133, off
	v_add_f32_e32 v228, v11, v11
	v_mul_f32_e32 v228, 0x3fb8aa3b, v228
	v_exp_f32_e32 v228, v228
	s_nop 0
	v_add_f32_e32 v229, 1.0, v228
	v_div_scale_f32 v230, s[4:5], v229, v229, 2.0
	v_rcp_f32_e32 v231, v230
	v_div_scale_f32 v232, vcc, 2.0, v229, 2.0
	v_fma_f32 v131, -v230, v231, 1.0
	v_fmac_f32_e32 v231, v131, v231
	v_mul_f32_e32 v233, v232, v231
	v_fma_f32 v131, -v230, v233, v232
	v_fmac_f32_e32 v233, v131, v231
	v_fma_f32 v230, -v230, v233, v232
	v_div_fmas_f32 v230, v230, v231, v233
	v_div_fixup_f32 v135, v230, v229, 2.0
	v_sub_f32_e32 v135, 1.0, v135
	v_add_f32_e32 v228, v15, v15
	v_mul_f32_e32 v228, 0x3fb8aa3b, v228
	v_exp_f32_e32 v228, v228
	s_nop 0
	v_add_f32_e32 v229, 1.0, v228
	v_div_scale_f32 v230, s[4:5], v229, v229, 2.0
	v_rcp_f32_e32 v231, v230
	v_div_scale_f32 v232, vcc, 2.0, v229, 2.0
	v_fma_f32 v131, -v230, v231, 1.0
	v_fmac_f32_e32 v231, v131, v231
	v_mul_f32_e32 v233, v232, v231
	v_fma_f32 v131, -v230, v233, v232
	v_fmac_f32_e32 v233, v131, v231
	v_fma_f32 v230, -v230, v233, v232
	v_div_fmas_f32 v230, v230, v231, v233
	v_div_fixup_f32 v133, v230, v229, 2.0
	v_sub_f32_e32 v133, 1.0, v133
	v_cvt_pk_bf16_f32 v133, v135, v133
	global_store_dword v[226:227], v133, off offset:64
	s_mov_b64 s[4:5], 0x2700
	v_lshl_add_u64 v[226:227], v[226:227], 0, s[4:5]
	v_add_f32_e32 v228, v16, v16
	v_mul_f32_e32 v228, 0x3fb8aa3b, v228
	v_exp_f32_e32 v228, v228
	s_nop 0
	v_add_f32_e32 v229, 1.0, v228
	v_div_scale_f32 v230, s[4:5], v229, v229, 2.0
	v_rcp_f32_e32 v231, v230
	v_div_scale_f32 v232, vcc, 2.0, v229, 2.0
	v_fma_f32 v131, -v230, v231, 1.0
	v_fmac_f32_e32 v231, v131, v231
	v_mul_f32_e32 v233, v232, v231
	v_fma_f32 v131, -v230, v233, v232
	v_fmac_f32_e32 v233, v131, v231
	v_fma_f32 v230, -v230, v233, v232
	v_div_fmas_f32 v230, v230, v231, v233
	v_div_fixup_f32 v135, v230, v229, 2.0
	v_sub_f32_e32 v135, 1.0, v135
	v_add_f32_e32 v228, v20, v20
	v_mul_f32_e32 v228, 0x3fb8aa3b, v228
	v_exp_f32_e32 v228, v228
	s_nop 0
	v_add_f32_e32 v229, 1.0, v228
	v_div_scale_f32 v230, s[4:5], v229, v229, 2.0
	v_rcp_f32_e32 v231, v230
	v_div_scale_f32 v232, vcc, 2.0, v229, 2.0
	v_fma_f32 v131, -v230, v231, 1.0
	v_fmac_f32_e32 v231, v131, v231
	v_mul_f32_e32 v233, v232, v231
	v_fma_f32 v131, -v230, v233, v232
	v_fmac_f32_e32 v233, v131, v231
	v_fma_f32 v230, -v230, v233, v232
	v_div_fmas_f32 v230, v230, v231, v233
	v_div_fixup_f32 v133, v230, v229, 2.0
	v_sub_f32_e32 v133, 1.0, v133
	v_cvt_pk_bf16_f32 v133, v135, v133
	global_store_dword v[226:227], v133, off
	v_add_f32_e32 v228, v24, v24
	v_mul_f32_e32 v228, 0x3fb8aa3b, v228
	v_exp_f32_e32 v228, v228
	s_nop 0
	v_add_f32_e32 v229, 1.0, v228
	v_div_scale_f32 v230, s[4:5], v229, v229, 2.0
	v_rcp_f32_e32 v231, v230
	v_div_scale_f32 v232, vcc, 2.0, v229, 2.0
	v_fma_f32 v131, -v230, v231, 1.0
	v_fmac_f32_e32 v231, v131, v231
	v_mul_f32_e32 v233, v232, v231
	v_fma_f32 v131, -v230, v233, v232
	v_fmac_f32_e32 v233, v131, v231
	v_fma_f32 v230, -v230, v233, v232
	v_div_fmas_f32 v230, v230, v231, v233
	v_div_fixup_f32 v135, v230, v229, 2.0
	v_sub_f32_e32 v135, 1.0, v135
	v_add_f32_e32 v228, v28, v28
	v_mul_f32_e32 v228, 0x3fb8aa3b, v228
	v_exp_f32_e32 v228, v228
	s_nop 0
	v_add_f32_e32 v229, 1.0, v228
	v_div_scale_f32 v230, s[4:5], v229, v229, 2.0
	v_rcp_f32_e32 v231, v230
	v_div_scale_f32 v232, vcc, 2.0, v229, 2.0
	v_fma_f32 v131, -v230, v231, 1.0
	v_fmac_f32_e32 v231, v131, v231
	v_mul_f32_e32 v233, v232, v231
	v_fma_f32 v131, -v230, v233, v232
	v_fmac_f32_e32 v233, v131, v231
	v_fma_f32 v230, -v230, v233, v232
	v_div_fmas_f32 v230, v230, v231, v233
	v_div_fixup_f32 v133, v230, v229, 2.0
	v_sub_f32_e32 v133, 1.0, v133
	v_cvt_pk_bf16_f32 v133, v135, v133
	global_store_dword v[226:227], v133, off offset:64
	s_mov_b64 s[4:5], 0x300
	v_lshl_add_u64 v[226:227], v[226:227], 0, s[4:5]
	v_add_f32_e32 v228, v17, v17
	v_mul_f32_e32 v228, 0x3fb8aa3b, v228
	v_exp_f32_e32 v228, v228
	s_nop 0
	v_add_f32_e32 v229, 1.0, v228
	v_div_scale_f32 v230, s[4:5], v229, v229, 2.0
	v_rcp_f32_e32 v231, v230
	v_div_scale_f32 v232, vcc, 2.0, v229, 2.0
	v_fma_f32 v131, -v230, v231, 1.0
	v_fmac_f32_e32 v231, v131, v231
	v_mul_f32_e32 v233, v232, v231
	v_fma_f32 v131, -v230, v233, v232
	v_fmac_f32_e32 v233, v131, v231
	v_fma_f32 v230, -v230, v233, v232
	v_div_fmas_f32 v230, v230, v231, v233
	v_div_fixup_f32 v135, v230, v229, 2.0
	v_sub_f32_e32 v135, 1.0, v135
	v_add_f32_e32 v228, v21, v21
	v_mul_f32_e32 v228, 0x3fb8aa3b, v228
	v_exp_f32_e32 v228, v228
	s_nop 0
	v_add_f32_e32 v229, 1.0, v228
	v_div_scale_f32 v230, s[4:5], v229, v229, 2.0
	v_rcp_f32_e32 v231, v230
	v_div_scale_f32 v232, vcc, 2.0, v229, 2.0
	v_fma_f32 v131, -v230, v231, 1.0
	v_fmac_f32_e32 v231, v131, v231
	v_mul_f32_e32 v233, v232, v231
	v_fma_f32 v131, -v230, v233, v232
	v_fmac_f32_e32 v233, v131, v231
	v_fma_f32 v230, -v230, v233, v232
	v_div_fmas_f32 v230, v230, v231, v233
	v_div_fixup_f32 v133, v230, v229, 2.0
	v_sub_f32_e32 v133, 1.0, v133
	v_cvt_pk_bf16_f32 v133, v135, v133
	global_store_dword v[226:227], v133, off
	v_add_f32_e32 v228, v25, v25
	v_mul_f32_e32 v228, 0x3fb8aa3b, v228
	v_exp_f32_e32 v228, v228
	s_nop 0
	v_add_f32_e32 v229, 1.0, v228
	v_div_scale_f32 v230, s[4:5], v229, v229, 2.0
	v_rcp_f32_e32 v231, v230
	v_div_scale_f32 v232, vcc, 2.0, v229, 2.0
	v_fma_f32 v131, -v230, v231, 1.0
	v_fmac_f32_e32 v231, v131, v231
	v_mul_f32_e32 v233, v232, v231
	v_fma_f32 v131, -v230, v233, v232
	v_fmac_f32_e32 v233, v131, v231
	v_fma_f32 v230, -v230, v233, v232
	v_div_fmas_f32 v230, v230, v231, v233
	v_div_fixup_f32 v135, v230, v229, 2.0
	v_sub_f32_e32 v135, 1.0, v135
	v_add_f32_e32 v228, v29, v29
	v_mul_f32_e32 v228, 0x3fb8aa3b, v228
	v_exp_f32_e32 v228, v228
	s_nop 0
	v_add_f32_e32 v229, 1.0, v228
	v_div_scale_f32 v230, s[4:5], v229, v229, 2.0
	v_rcp_f32_e32 v231, v230
	v_div_scale_f32 v232, vcc, 2.0, v229, 2.0
	v_fma_f32 v131, -v230, v231, 1.0
	v_fmac_f32_e32 v231, v131, v231
	v_mul_f32_e32 v233, v232, v231
	v_fma_f32 v131, -v230, v233, v232
	v_fmac_f32_e32 v233, v131, v231
	v_fma_f32 v230, -v230, v233, v232
	v_div_fmas_f32 v230, v230, v231, v233
	v_div_fixup_f32 v133, v230, v229, 2.0
	v_sub_f32_e32 v133, 1.0, v133
	v_cvt_pk_bf16_f32 v133, v135, v133
	global_store_dword v[226:227], v133, off offset:64
	s_mov_b64 s[4:5], 0x300
	v_lshl_add_u64 v[226:227], v[226:227], 0, s[4:5]
	v_add_f32_e32 v228, v18, v18
	v_mul_f32_e32 v228, 0x3fb8aa3b, v228
	v_exp_f32_e32 v228, v228
	s_nop 0
	v_add_f32_e32 v229, 1.0, v228
	v_div_scale_f32 v230, s[4:5], v229, v229, 2.0
	v_rcp_f32_e32 v231, v230
	v_div_scale_f32 v232, vcc, 2.0, v229, 2.0
	v_fma_f32 v131, -v230, v231, 1.0
	v_fmac_f32_e32 v231, v131, v231
	v_mul_f32_e32 v233, v232, v231
	v_fma_f32 v131, -v230, v233, v232
	v_fmac_f32_e32 v233, v131, v231
	v_fma_f32 v230, -v230, v233, v232
	v_div_fmas_f32 v230, v230, v231, v233
	v_div_fixup_f32 v135, v230, v229, 2.0
	v_sub_f32_e32 v135, 1.0, v135
	v_add_f32_e32 v228, v22, v22
	v_mul_f32_e32 v228, 0x3fb8aa3b, v228
	v_exp_f32_e32 v228, v228
	s_nop 0
	v_add_f32_e32 v229, 1.0, v228
	v_div_scale_f32 v230, s[4:5], v229, v229, 2.0
	v_rcp_f32_e32 v231, v230
	v_div_scale_f32 v232, vcc, 2.0, v229, 2.0
	v_fma_f32 v131, -v230, v231, 1.0
	v_fmac_f32_e32 v231, v131, v231
	v_mul_f32_e32 v233, v232, v231
	v_fma_f32 v131, -v230, v233, v232
	v_fmac_f32_e32 v233, v131, v231
	v_fma_f32 v230, -v230, v233, v232
	v_div_fmas_f32 v230, v230, v231, v233
	v_div_fixup_f32 v133, v230, v229, 2.0
	v_sub_f32_e32 v133, 1.0, v133
	v_cvt_pk_bf16_f32 v133, v135, v133
	global_store_dword v[226:227], v133, off
	v_add_f32_e32 v228, v26, v26
	v_mul_f32_e32 v228, 0x3fb8aa3b, v228
	v_exp_f32_e32 v228, v228
	s_nop 0
	v_add_f32_e32 v229, 1.0, v228
	v_div_scale_f32 v230, s[4:5], v229, v229, 2.0
	v_rcp_f32_e32 v231, v230
	v_div_scale_f32 v232, vcc, 2.0, v229, 2.0
	v_fma_f32 v131, -v230, v231, 1.0
	v_fmac_f32_e32 v231, v131, v231
	v_mul_f32_e32 v233, v232, v231
	v_fma_f32 v131, -v230, v233, v232
	v_fmac_f32_e32 v233, v131, v231
	v_fma_f32 v230, -v230, v233, v232
	v_div_fmas_f32 v230, v230, v231, v233
	v_div_fixup_f32 v135, v230, v229, 2.0
	v_sub_f32_e32 v135, 1.0, v135
	v_add_f32_e32 v228, v30, v30
	v_mul_f32_e32 v228, 0x3fb8aa3b, v228
	v_exp_f32_e32 v228, v228
	s_nop 0
	v_add_f32_e32 v229, 1.0, v228
	v_div_scale_f32 v230, s[4:5], v229, v229, 2.0
	v_rcp_f32_e32 v231, v230
	v_div_scale_f32 v232, vcc, 2.0, v229, 2.0
	v_fma_f32 v131, -v230, v231, 1.0
	v_fmac_f32_e32 v231, v131, v231
	v_mul_f32_e32 v233, v232, v231
	v_fma_f32 v131, -v230, v233, v232
	v_fmac_f32_e32 v233, v131, v231
	v_fma_f32 v230, -v230, v233, v232
	v_div_fmas_f32 v230, v230, v231, v233
	v_div_fixup_f32 v133, v230, v229, 2.0
	v_sub_f32_e32 v133, 1.0, v133
	v_cvt_pk_bf16_f32 v133, v135, v133
	global_store_dword v[226:227], v133, off offset:64
	s_mov_b64 s[4:5], 0x300
	v_lshl_add_u64 v[226:227], v[226:227], 0, s[4:5]
	v_add_f32_e32 v228, v19, v19
	v_mul_f32_e32 v228, 0x3fb8aa3b, v228
	v_exp_f32_e32 v228, v228
	s_nop 0
	v_add_f32_e32 v229, 1.0, v228
	v_div_scale_f32 v230, s[4:5], v229, v229, 2.0
	v_rcp_f32_e32 v231, v230
	v_div_scale_f32 v232, vcc, 2.0, v229, 2.0
	v_fma_f32 v131, -v230, v231, 1.0
	v_fmac_f32_e32 v231, v131, v231
	v_mul_f32_e32 v233, v232, v231
	v_fma_f32 v131, -v230, v233, v232
	v_fmac_f32_e32 v233, v131, v231
	v_fma_f32 v230, -v230, v233, v232
	v_div_fmas_f32 v230, v230, v231, v233
	v_div_fixup_f32 v135, v230, v229, 2.0
	v_sub_f32_e32 v135, 1.0, v135
	v_add_f32_e32 v228, v23, v23
	v_mul_f32_e32 v228, 0x3fb8aa3b, v228
	v_exp_f32_e32 v228, v228
	s_nop 0
	v_add_f32_e32 v229, 1.0, v228
	v_div_scale_f32 v230, s[4:5], v229, v229, 2.0
	v_rcp_f32_e32 v231, v230
	v_div_scale_f32 v232, vcc, 2.0, v229, 2.0
	v_fma_f32 v131, -v230, v231, 1.0
	v_fmac_f32_e32 v231, v131, v231
	v_mul_f32_e32 v233, v232, v231
	v_fma_f32 v131, -v230, v233, v232
	v_fmac_f32_e32 v233, v131, v231
	v_fma_f32 v230, -v230, v233, v232
	v_div_fmas_f32 v230, v230, v231, v233
	v_div_fixup_f32 v133, v230, v229, 2.0
	v_sub_f32_e32 v133, 1.0, v133
	v_cvt_pk_bf16_f32 v133, v135, v133
	global_store_dword v[226:227], v133, off
	v_add_f32_e32 v228, v27, v27
	v_mul_f32_e32 v228, 0x3fb8aa3b, v228
	v_exp_f32_e32 v228, v228
	s_nop 0
	v_add_f32_e32 v229, 1.0, v228
	v_div_scale_f32 v230, s[4:5], v229, v229, 2.0
	v_rcp_f32_e32 v231, v230
	v_div_scale_f32 v232, vcc, 2.0, v229, 2.0
	v_fma_f32 v131, -v230, v231, 1.0
	v_fmac_f32_e32 v231, v131, v231
	v_mul_f32_e32 v233, v232, v231
	v_fma_f32 v131, -v230, v233, v232
	v_fmac_f32_e32 v233, v131, v231
	v_fma_f32 v230, -v230, v233, v232
	v_div_fmas_f32 v230, v230, v231, v233
	v_div_fixup_f32 v135, v230, v229, 2.0
	v_sub_f32_e32 v135, 1.0, v135
	v_add_f32_e32 v228, v31, v31
	v_mul_f32_e32 v228, 0x3fb8aa3b, v228
	v_exp_f32_e32 v228, v228
	s_nop 0
	v_add_f32_e32 v229, 1.0, v228
	v_div_scale_f32 v230, s[4:5], v229, v229, 2.0
	v_rcp_f32_e32 v231, v230
	v_div_scale_f32 v232, vcc, 2.0, v229, 2.0
	v_fma_f32 v131, -v230, v231, 1.0
	v_fmac_f32_e32 v231, v131, v231
	v_mul_f32_e32 v233, v232, v231
	v_fma_f32 v131, -v230, v233, v232
	v_fmac_f32_e32 v233, v131, v231
	v_fma_f32 v230, -v230, v233, v232
	v_div_fmas_f32 v230, v230, v231, v233
	v_div_fixup_f32 v133, v230, v229, 2.0
	v_sub_f32_e32 v133, 1.0, v133
	v_cvt_pk_bf16_f32 v133, v135, v133
	global_store_dword v[226:227], v133, off offset:64
	s_mov_b64 s[4:5], 0x2700
	v_lshl_add_u64 v[226:227], v[226:227], 0, s[4:5]
	v_add_f32_e32 v228, v32, v32
	v_mul_f32_e32 v228, 0x3fb8aa3b, v228
	v_exp_f32_e32 v228, v228
	s_nop 0
	v_add_f32_e32 v229, 1.0, v228
	v_div_scale_f32 v230, s[4:5], v229, v229, 2.0
	v_rcp_f32_e32 v231, v230
	v_div_scale_f32 v232, vcc, 2.0, v229, 2.0
	v_fma_f32 v131, -v230, v231, 1.0
	v_fmac_f32_e32 v231, v131, v231
	v_mul_f32_e32 v233, v232, v231
	v_fma_f32 v131, -v230, v233, v232
	v_fmac_f32_e32 v233, v131, v231
	v_fma_f32 v230, -v230, v233, v232
	v_div_fmas_f32 v230, v230, v231, v233
	v_div_fixup_f32 v135, v230, v229, 2.0
	v_sub_f32_e32 v135, 1.0, v135
	v_add_f32_e32 v228, v36, v36
	v_mul_f32_e32 v228, 0x3fb8aa3b, v228
	v_exp_f32_e32 v228, v228
	s_nop 0
	v_add_f32_e32 v229, 1.0, v228
	v_div_scale_f32 v230, s[4:5], v229, v229, 2.0
	v_rcp_f32_e32 v231, v230
	v_div_scale_f32 v232, vcc, 2.0, v229, 2.0
	v_fma_f32 v131, -v230, v231, 1.0
	v_fmac_f32_e32 v231, v131, v231
	v_mul_f32_e32 v233, v232, v231
	v_fma_f32 v131, -v230, v233, v232
	v_fmac_f32_e32 v233, v131, v231
	v_fma_f32 v230, -v230, v233, v232
	v_div_fmas_f32 v230, v230, v231, v233
	v_div_fixup_f32 v133, v230, v229, 2.0
	v_sub_f32_e32 v133, 1.0, v133
	v_cvt_pk_bf16_f32 v133, v135, v133
	global_store_dword v[226:227], v133, off
	v_add_f32_e32 v228, v40, v40
	v_mul_f32_e32 v228, 0x3fb8aa3b, v228
	v_exp_f32_e32 v228, v228
	s_nop 0
	v_add_f32_e32 v229, 1.0, v228
	v_div_scale_f32 v230, s[4:5], v229, v229, 2.0
	v_rcp_f32_e32 v231, v230
	v_div_scale_f32 v232, vcc, 2.0, v229, 2.0
	v_fma_f32 v131, -v230, v231, 1.0
	v_fmac_f32_e32 v231, v131, v231
	v_mul_f32_e32 v233, v232, v231
	v_fma_f32 v131, -v230, v233, v232
	v_fmac_f32_e32 v233, v131, v231
	v_fma_f32 v230, -v230, v233, v232
	v_div_fmas_f32 v230, v230, v231, v233
	v_div_fixup_f32 v135, v230, v229, 2.0
	v_sub_f32_e32 v135, 1.0, v135
	v_add_f32_e32 v228, v44, v44
	v_mul_f32_e32 v228, 0x3fb8aa3b, v228
	v_exp_f32_e32 v228, v228
	s_nop 0
	v_add_f32_e32 v229, 1.0, v228
	v_div_scale_f32 v230, s[4:5], v229, v229, 2.0
	v_rcp_f32_e32 v231, v230
	v_div_scale_f32 v232, vcc, 2.0, v229, 2.0
	v_fma_f32 v131, -v230, v231, 1.0
	v_fmac_f32_e32 v231, v131, v231
	v_mul_f32_e32 v233, v232, v231
	v_fma_f32 v131, -v230, v233, v232
	v_fmac_f32_e32 v233, v131, v231
	v_fma_f32 v230, -v230, v233, v232
	v_div_fmas_f32 v230, v230, v231, v233
	v_div_fixup_f32 v133, v230, v229, 2.0
	v_sub_f32_e32 v133, 1.0, v133
	v_cvt_pk_bf16_f32 v133, v135, v133
	global_store_dword v[226:227], v133, off offset:64
	s_mov_b64 s[4:5], 0x300
	v_lshl_add_u64 v[226:227], v[226:227], 0, s[4:5]
	v_add_f32_e32 v228, v33, v33
	v_mul_f32_e32 v228, 0x3fb8aa3b, v228
	v_exp_f32_e32 v228, v228
	s_nop 0
	v_add_f32_e32 v229, 1.0, v228
	v_div_scale_f32 v230, s[4:5], v229, v229, 2.0
	v_rcp_f32_e32 v231, v230
	v_div_scale_f32 v232, vcc, 2.0, v229, 2.0
	v_fma_f32 v131, -v230, v231, 1.0
	v_fmac_f32_e32 v231, v131, v231
	v_mul_f32_e32 v233, v232, v231
	v_fma_f32 v131, -v230, v233, v232
	v_fmac_f32_e32 v233, v131, v231
	v_fma_f32 v230, -v230, v233, v232
	v_div_fmas_f32 v230, v230, v231, v233
	v_div_fixup_f32 v135, v230, v229, 2.0
	v_sub_f32_e32 v135, 1.0, v135
	v_add_f32_e32 v228, v37, v37
	v_mul_f32_e32 v228, 0x3fb8aa3b, v228
	v_exp_f32_e32 v228, v228
	s_nop 0
	v_add_f32_e32 v229, 1.0, v228
	v_div_scale_f32 v230, s[4:5], v229, v229, 2.0
	v_rcp_f32_e32 v231, v230
	v_div_scale_f32 v232, vcc, 2.0, v229, 2.0
	v_fma_f32 v131, -v230, v231, 1.0
	v_fmac_f32_e32 v231, v131, v231
	v_mul_f32_e32 v233, v232, v231
	v_fma_f32 v131, -v230, v233, v232
	v_fmac_f32_e32 v233, v131, v231
	v_fma_f32 v230, -v230, v233, v232
	v_div_fmas_f32 v230, v230, v231, v233
	v_div_fixup_f32 v133, v230, v229, 2.0
	v_sub_f32_e32 v133, 1.0, v133
	v_cvt_pk_bf16_f32 v133, v135, v133
	global_store_dword v[226:227], v133, off
	v_add_f32_e32 v228, v41, v41
	v_mul_f32_e32 v228, 0x3fb8aa3b, v228
	v_exp_f32_e32 v228, v228
	s_nop 0
	v_add_f32_e32 v229, 1.0, v228
	v_div_scale_f32 v230, s[4:5], v229, v229, 2.0
	v_rcp_f32_e32 v231, v230
	v_div_scale_f32 v232, vcc, 2.0, v229, 2.0
	v_fma_f32 v131, -v230, v231, 1.0
	v_fmac_f32_e32 v231, v131, v231
	v_mul_f32_e32 v233, v232, v231
	v_fma_f32 v131, -v230, v233, v232
	v_fmac_f32_e32 v233, v131, v231
	v_fma_f32 v230, -v230, v233, v232
	v_div_fmas_f32 v230, v230, v231, v233
	v_div_fixup_f32 v135, v230, v229, 2.0
	v_sub_f32_e32 v135, 1.0, v135
	v_add_f32_e32 v228, v45, v45
	v_mul_f32_e32 v228, 0x3fb8aa3b, v228
	v_exp_f32_e32 v228, v228
	s_nop 0
	v_add_f32_e32 v229, 1.0, v228
	v_div_scale_f32 v230, s[4:5], v229, v229, 2.0
	v_rcp_f32_e32 v231, v230
	v_div_scale_f32 v232, vcc, 2.0, v229, 2.0
	v_fma_f32 v131, -v230, v231, 1.0
	v_fmac_f32_e32 v231, v131, v231
	v_mul_f32_e32 v233, v232, v231
	v_fma_f32 v131, -v230, v233, v232
	v_fmac_f32_e32 v233, v131, v231
	v_fma_f32 v230, -v230, v233, v232
	v_div_fmas_f32 v230, v230, v231, v233
	v_div_fixup_f32 v133, v230, v229, 2.0
	v_sub_f32_e32 v133, 1.0, v133
	v_cvt_pk_bf16_f32 v133, v135, v133
	global_store_dword v[226:227], v133, off offset:64
	s_mov_b64 s[4:5], 0x300
	v_lshl_add_u64 v[226:227], v[226:227], 0, s[4:5]
	v_add_f32_e32 v228, v34, v34
	v_mul_f32_e32 v228, 0x3fb8aa3b, v228
	v_exp_f32_e32 v228, v228
	s_nop 0
	v_add_f32_e32 v229, 1.0, v228
	v_div_scale_f32 v230, s[4:5], v229, v229, 2.0
	v_rcp_f32_e32 v231, v230
	v_div_scale_f32 v232, vcc, 2.0, v229, 2.0
	v_fma_f32 v131, -v230, v231, 1.0
	v_fmac_f32_e32 v231, v131, v231
	v_mul_f32_e32 v233, v232, v231
	v_fma_f32 v131, -v230, v233, v232
	v_fmac_f32_e32 v233, v131, v231
	v_fma_f32 v230, -v230, v233, v232
	v_div_fmas_f32 v230, v230, v231, v233
	v_div_fixup_f32 v135, v230, v229, 2.0
	v_sub_f32_e32 v135, 1.0, v135
	v_add_f32_e32 v228, v38, v38
	v_mul_f32_e32 v228, 0x3fb8aa3b, v228
	v_exp_f32_e32 v228, v228
	s_nop 0
	v_add_f32_e32 v229, 1.0, v228
	v_div_scale_f32 v230, s[4:5], v229, v229, 2.0
	v_rcp_f32_e32 v231, v230
	v_div_scale_f32 v232, vcc, 2.0, v229, 2.0
	v_fma_f32 v131, -v230, v231, 1.0
	v_fmac_f32_e32 v231, v131, v231
	v_mul_f32_e32 v233, v232, v231
	v_fma_f32 v131, -v230, v233, v232
	v_fmac_f32_e32 v233, v131, v231
	v_fma_f32 v230, -v230, v233, v232
	v_div_fmas_f32 v230, v230, v231, v233
	v_div_fixup_f32 v133, v230, v229, 2.0
	v_sub_f32_e32 v133, 1.0, v133
	v_cvt_pk_bf16_f32 v133, v135, v133
	global_store_dword v[226:227], v133, off
	v_add_f32_e32 v228, v42, v42
	v_mul_f32_e32 v228, 0x3fb8aa3b, v228
	v_exp_f32_e32 v228, v228
	s_nop 0
	v_add_f32_e32 v229, 1.0, v228
	v_div_scale_f32 v230, s[4:5], v229, v229, 2.0
	v_rcp_f32_e32 v231, v230
	v_div_scale_f32 v232, vcc, 2.0, v229, 2.0
	v_fma_f32 v131, -v230, v231, 1.0
	v_fmac_f32_e32 v231, v131, v231
	v_mul_f32_e32 v233, v232, v231
	v_fma_f32 v131, -v230, v233, v232
	v_fmac_f32_e32 v233, v131, v231
	v_fma_f32 v230, -v230, v233, v232
	v_div_fmas_f32 v230, v230, v231, v233
	v_div_fixup_f32 v135, v230, v229, 2.0
	v_sub_f32_e32 v135, 1.0, v135
	v_add_f32_e32 v228, v46, v46
	v_mul_f32_e32 v228, 0x3fb8aa3b, v228
	v_exp_f32_e32 v228, v228
	s_nop 0
	v_add_f32_e32 v229, 1.0, v228
	v_div_scale_f32 v230, s[4:5], v229, v229, 2.0
	v_rcp_f32_e32 v231, v230
	v_div_scale_f32 v232, vcc, 2.0, v229, 2.0
	v_fma_f32 v131, -v230, v231, 1.0
	v_fmac_f32_e32 v231, v131, v231
	v_mul_f32_e32 v233, v232, v231
	v_fma_f32 v131, -v230, v233, v232
	v_fmac_f32_e32 v233, v131, v231
	v_fma_f32 v230, -v230, v233, v232
	v_div_fmas_f32 v230, v230, v231, v233
	v_div_fixup_f32 v133, v230, v229, 2.0
	v_sub_f32_e32 v133, 1.0, v133
	v_cvt_pk_bf16_f32 v133, v135, v133
	global_store_dword v[226:227], v133, off offset:64
	s_mov_b64 s[4:5], 0x300
	v_lshl_add_u64 v[226:227], v[226:227], 0, s[4:5]
	v_add_f32_e32 v228, v35, v35
	v_mul_f32_e32 v228, 0x3fb8aa3b, v228
	v_exp_f32_e32 v228, v228
	s_nop 0
	v_add_f32_e32 v229, 1.0, v228
	v_div_scale_f32 v230, s[4:5], v229, v229, 2.0
	v_rcp_f32_e32 v231, v230
	v_div_scale_f32 v232, vcc, 2.0, v229, 2.0
	v_fma_f32 v131, -v230, v231, 1.0
	v_fmac_f32_e32 v231, v131, v231
	v_mul_f32_e32 v233, v232, v231
	v_fma_f32 v131, -v230, v233, v232
	v_fmac_f32_e32 v233, v131, v231
	v_fma_f32 v230, -v230, v233, v232
	v_div_fmas_f32 v230, v230, v231, v233
	v_div_fixup_f32 v135, v230, v229, 2.0
	v_sub_f32_e32 v135, 1.0, v135
	v_add_f32_e32 v228, v39, v39
	v_mul_f32_e32 v228, 0x3fb8aa3b, v228
	v_exp_f32_e32 v228, v228
	s_nop 0
	v_add_f32_e32 v229, 1.0, v228
	v_div_scale_f32 v230, s[4:5], v229, v229, 2.0
	v_rcp_f32_e32 v231, v230
	v_div_scale_f32 v232, vcc, 2.0, v229, 2.0
	v_fma_f32 v131, -v230, v231, 1.0
	v_fmac_f32_e32 v231, v131, v231
	v_mul_f32_e32 v233, v232, v231
	v_fma_f32 v131, -v230, v233, v232
	v_fmac_f32_e32 v233, v131, v231
	v_fma_f32 v230, -v230, v233, v232
	v_div_fmas_f32 v230, v230, v231, v233
	v_div_fixup_f32 v133, v230, v229, 2.0
	v_sub_f32_e32 v133, 1.0, v133
	v_cvt_pk_bf16_f32 v133, v135, v133
	global_store_dword v[226:227], v133, off
	v_add_f32_e32 v228, v43, v43
	v_mul_f32_e32 v228, 0x3fb8aa3b, v228
	v_exp_f32_e32 v228, v228
	s_nop 0
	v_add_f32_e32 v229, 1.0, v228
	v_div_scale_f32 v230, s[4:5], v229, v229, 2.0
	v_rcp_f32_e32 v231, v230
	v_div_scale_f32 v232, vcc, 2.0, v229, 2.0
	v_fma_f32 v131, -v230, v231, 1.0
	v_fmac_f32_e32 v231, v131, v231
	v_mul_f32_e32 v233, v232, v231
	v_fma_f32 v131, -v230, v233, v232
	v_fmac_f32_e32 v233, v131, v231
	v_fma_f32 v230, -v230, v233, v232
	v_div_fmas_f32 v230, v230, v231, v233
	v_div_fixup_f32 v135, v230, v229, 2.0
	v_sub_f32_e32 v135, 1.0, v135
	v_add_f32_e32 v228, v47, v47
	v_mul_f32_e32 v228, 0x3fb8aa3b, v228
	v_exp_f32_e32 v228, v228
	s_nop 0
	v_add_f32_e32 v229, 1.0, v228
	v_div_scale_f32 v230, s[4:5], v229, v229, 2.0
	v_rcp_f32_e32 v231, v230
	v_div_scale_f32 v232, vcc, 2.0, v229, 2.0
	v_fma_f32 v131, -v230, v231, 1.0
	v_fmac_f32_e32 v231, v131, v231
	v_mul_f32_e32 v233, v232, v231
	v_fma_f32 v131, -v230, v233, v232
	v_fmac_f32_e32 v233, v131, v231
	v_fma_f32 v230, -v230, v233, v232
	v_div_fmas_f32 v230, v230, v231, v233
	v_div_fixup_f32 v133, v230, v229, 2.0
	v_sub_f32_e32 v133, 1.0, v133
	v_cvt_pk_bf16_f32 v133, v135, v133
	global_store_dword v[226:227], v133, off offset:64
	s_mov_b64 s[4:5], 0x2700
	v_lshl_add_u64 v[226:227], v[226:227], 0, s[4:5]
	v_add_f32_e32 v228, v48, v48
	v_mul_f32_e32 v228, 0x3fb8aa3b, v228
	v_exp_f32_e32 v228, v228
	s_nop 0
	v_add_f32_e32 v229, 1.0, v228
	v_div_scale_f32 v230, s[4:5], v229, v229, 2.0
	v_rcp_f32_e32 v231, v230
	v_div_scale_f32 v232, vcc, 2.0, v229, 2.0
	v_fma_f32 v131, -v230, v231, 1.0
	v_fmac_f32_e32 v231, v131, v231
	v_mul_f32_e32 v233, v232, v231
	v_fma_f32 v131, -v230, v233, v232
	v_fmac_f32_e32 v233, v131, v231
	v_fma_f32 v230, -v230, v233, v232
	v_div_fmas_f32 v230, v230, v231, v233
	v_div_fixup_f32 v135, v230, v229, 2.0
	v_sub_f32_e32 v135, 1.0, v135
	v_add_f32_e32 v228, v52, v52
	v_mul_f32_e32 v228, 0x3fb8aa3b, v228
	v_exp_f32_e32 v228, v228
	s_nop 0
	v_add_f32_e32 v229, 1.0, v228
	v_div_scale_f32 v230, s[4:5], v229, v229, 2.0
	v_rcp_f32_e32 v231, v230
	v_div_scale_f32 v232, vcc, 2.0, v229, 2.0
	v_fma_f32 v131, -v230, v231, 1.0
	v_fmac_f32_e32 v231, v131, v231
	v_mul_f32_e32 v233, v232, v231
	v_fma_f32 v131, -v230, v233, v232
	v_fmac_f32_e32 v233, v131, v231
	v_fma_f32 v230, -v230, v233, v232
	v_div_fmas_f32 v230, v230, v231, v233
	v_div_fixup_f32 v133, v230, v229, 2.0
	v_sub_f32_e32 v133, 1.0, v133
	v_cvt_pk_bf16_f32 v133, v135, v133
	global_store_dword v[226:227], v133, off
	v_add_f32_e32 v228, v56, v56
	v_mul_f32_e32 v228, 0x3fb8aa3b, v228
	v_exp_f32_e32 v228, v228
	s_nop 0
	v_add_f32_e32 v229, 1.0, v228
	v_div_scale_f32 v230, s[4:5], v229, v229, 2.0
	v_rcp_f32_e32 v231, v230
	v_div_scale_f32 v232, vcc, 2.0, v229, 2.0
	v_fma_f32 v131, -v230, v231, 1.0
	v_fmac_f32_e32 v231, v131, v231
	v_mul_f32_e32 v233, v232, v231
	v_fma_f32 v131, -v230, v233, v232
	v_fmac_f32_e32 v233, v131, v231
	v_fma_f32 v230, -v230, v233, v232
	v_div_fmas_f32 v230, v230, v231, v233
	v_div_fixup_f32 v135, v230, v229, 2.0
	v_sub_f32_e32 v135, 1.0, v135
	v_add_f32_e32 v228, v60, v60
	v_mul_f32_e32 v228, 0x3fb8aa3b, v228
	v_exp_f32_e32 v228, v228
	s_nop 0
	v_add_f32_e32 v229, 1.0, v228
	v_div_scale_f32 v230, s[4:5], v229, v229, 2.0
	v_rcp_f32_e32 v231, v230
	v_div_scale_f32 v232, vcc, 2.0, v229, 2.0
	v_fma_f32 v131, -v230, v231, 1.0
	v_fmac_f32_e32 v231, v131, v231
	v_mul_f32_e32 v233, v232, v231
	v_fma_f32 v131, -v230, v233, v232
	v_fmac_f32_e32 v233, v131, v231
	v_fma_f32 v230, -v230, v233, v232
	v_div_fmas_f32 v230, v230, v231, v233
	v_div_fixup_f32 v133, v230, v229, 2.0
	v_sub_f32_e32 v133, 1.0, v133
	v_cvt_pk_bf16_f32 v133, v135, v133
	global_store_dword v[226:227], v133, off offset:64
	s_mov_b64 s[4:5], 0x300
	v_lshl_add_u64 v[226:227], v[226:227], 0, s[4:5]
	v_add_f32_e32 v228, v49, v49
	v_mul_f32_e32 v228, 0x3fb8aa3b, v228
	v_exp_f32_e32 v228, v228
	s_nop 0
	v_add_f32_e32 v229, 1.0, v228
	v_div_scale_f32 v230, s[4:5], v229, v229, 2.0
	v_rcp_f32_e32 v231, v230
	v_div_scale_f32 v232, vcc, 2.0, v229, 2.0
	v_fma_f32 v131, -v230, v231, 1.0
	v_fmac_f32_e32 v231, v131, v231
	v_mul_f32_e32 v233, v232, v231
	v_fma_f32 v131, -v230, v233, v232
	v_fmac_f32_e32 v233, v131, v231
	v_fma_f32 v230, -v230, v233, v232
	v_div_fmas_f32 v230, v230, v231, v233
	v_div_fixup_f32 v135, v230, v229, 2.0
	v_sub_f32_e32 v135, 1.0, v135
	v_add_f32_e32 v228, v53, v53
	v_mul_f32_e32 v228, 0x3fb8aa3b, v228
	v_exp_f32_e32 v228, v228
	s_nop 0
	v_add_f32_e32 v229, 1.0, v228
	v_div_scale_f32 v230, s[4:5], v229, v229, 2.0
	v_rcp_f32_e32 v231, v230
	v_div_scale_f32 v232, vcc, 2.0, v229, 2.0
	v_fma_f32 v131, -v230, v231, 1.0
	v_fmac_f32_e32 v231, v131, v231
	v_mul_f32_e32 v233, v232, v231
	v_fma_f32 v131, -v230, v233, v232
	v_fmac_f32_e32 v233, v131, v231
	v_fma_f32 v230, -v230, v233, v232
	v_div_fmas_f32 v230, v230, v231, v233
	v_div_fixup_f32 v133, v230, v229, 2.0
	v_sub_f32_e32 v133, 1.0, v133
	v_cvt_pk_bf16_f32 v133, v135, v133
	global_store_dword v[226:227], v133, off
	v_add_f32_e32 v228, v57, v57
	v_mul_f32_e32 v228, 0x3fb8aa3b, v228
	v_exp_f32_e32 v228, v228
	s_nop 0
	v_add_f32_e32 v229, 1.0, v228
	v_div_scale_f32 v230, s[4:5], v229, v229, 2.0
	v_rcp_f32_e32 v231, v230
	v_div_scale_f32 v232, vcc, 2.0, v229, 2.0
	v_fma_f32 v131, -v230, v231, 1.0
	v_fmac_f32_e32 v231, v131, v231
	v_mul_f32_e32 v233, v232, v231
	v_fma_f32 v131, -v230, v233, v232
	v_fmac_f32_e32 v233, v131, v231
	v_fma_f32 v230, -v230, v233, v232
	v_div_fmas_f32 v230, v230, v231, v233
	v_div_fixup_f32 v135, v230, v229, 2.0
	v_sub_f32_e32 v135, 1.0, v135
	v_add_f32_e32 v228, v61, v61
	v_mul_f32_e32 v228, 0x3fb8aa3b, v228
	v_exp_f32_e32 v228, v228
	s_nop 0
	v_add_f32_e32 v229, 1.0, v228
	v_div_scale_f32 v230, s[4:5], v229, v229, 2.0
	v_rcp_f32_e32 v231, v230
	v_div_scale_f32 v232, vcc, 2.0, v229, 2.0
	v_fma_f32 v131, -v230, v231, 1.0
	v_fmac_f32_e32 v231, v131, v231
	v_mul_f32_e32 v233, v232, v231
	v_fma_f32 v131, -v230, v233, v232
	v_fmac_f32_e32 v233, v131, v231
	v_fma_f32 v230, -v230, v233, v232
	v_div_fmas_f32 v230, v230, v231, v233
	v_div_fixup_f32 v133, v230, v229, 2.0
	v_sub_f32_e32 v133, 1.0, v133
	v_cvt_pk_bf16_f32 v133, v135, v133
	global_store_dword v[226:227], v133, off offset:64
	s_mov_b64 s[4:5], 0x300
	v_lshl_add_u64 v[226:227], v[226:227], 0, s[4:5]
	v_add_f32_e32 v228, v50, v50
	v_mul_f32_e32 v228, 0x3fb8aa3b, v228
	v_exp_f32_e32 v228, v228
	s_nop 0
	v_add_f32_e32 v229, 1.0, v228
	v_div_scale_f32 v230, s[4:5], v229, v229, 2.0
	v_rcp_f32_e32 v231, v230
	v_div_scale_f32 v232, vcc, 2.0, v229, 2.0
	v_fma_f32 v131, -v230, v231, 1.0
	v_fmac_f32_e32 v231, v131, v231
	v_mul_f32_e32 v233, v232, v231
	v_fma_f32 v131, -v230, v233, v232
	v_fmac_f32_e32 v233, v131, v231
	v_fma_f32 v230, -v230, v233, v232
	v_div_fmas_f32 v230, v230, v231, v233
	v_div_fixup_f32 v135, v230, v229, 2.0
	v_sub_f32_e32 v135, 1.0, v135
	v_add_f32_e32 v228, v54, v54
	v_mul_f32_e32 v228, 0x3fb8aa3b, v228
	v_exp_f32_e32 v228, v228
	s_nop 0
	v_add_f32_e32 v229, 1.0, v228
	v_div_scale_f32 v230, s[4:5], v229, v229, 2.0
	v_rcp_f32_e32 v231, v230
	v_div_scale_f32 v232, vcc, 2.0, v229, 2.0
	v_fma_f32 v131, -v230, v231, 1.0
	v_fmac_f32_e32 v231, v131, v231
	v_mul_f32_e32 v233, v232, v231
	v_fma_f32 v131, -v230, v233, v232
	v_fmac_f32_e32 v233, v131, v231
	v_fma_f32 v230, -v230, v233, v232
	v_div_fmas_f32 v230, v230, v231, v233
	v_div_fixup_f32 v133, v230, v229, 2.0
	v_sub_f32_e32 v133, 1.0, v133
	v_cvt_pk_bf16_f32 v133, v135, v133
	global_store_dword v[226:227], v133, off
	v_add_f32_e32 v228, v58, v58
	v_mul_f32_e32 v228, 0x3fb8aa3b, v228
	v_exp_f32_e32 v228, v228
	s_nop 0
	v_add_f32_e32 v229, 1.0, v228
	v_div_scale_f32 v230, s[4:5], v229, v229, 2.0
	v_rcp_f32_e32 v231, v230
	v_div_scale_f32 v232, vcc, 2.0, v229, 2.0
	v_fma_f32 v131, -v230, v231, 1.0
	v_fmac_f32_e32 v231, v131, v231
	v_mul_f32_e32 v233, v232, v231
	v_fma_f32 v131, -v230, v233, v232
	v_fmac_f32_e32 v233, v131, v231
	v_fma_f32 v230, -v230, v233, v232
	v_div_fmas_f32 v230, v230, v231, v233
	v_div_fixup_f32 v135, v230, v229, 2.0
	v_sub_f32_e32 v135, 1.0, v135
	v_add_f32_e32 v228, v62, v62
	v_mul_f32_e32 v228, 0x3fb8aa3b, v228
	v_exp_f32_e32 v228, v228
	s_nop 0
	v_add_f32_e32 v229, 1.0, v228
	v_div_scale_f32 v230, s[4:5], v229, v229, 2.0
	v_rcp_f32_e32 v231, v230
	v_div_scale_f32 v232, vcc, 2.0, v229, 2.0
	v_fma_f32 v131, -v230, v231, 1.0
	v_fmac_f32_e32 v231, v131, v231
	v_mul_f32_e32 v233, v232, v231
	v_fma_f32 v131, -v230, v233, v232
	v_fmac_f32_e32 v233, v131, v231
	v_fma_f32 v230, -v230, v233, v232
	v_div_fmas_f32 v230, v230, v231, v233
	v_div_fixup_f32 v133, v230, v229, 2.0
	v_sub_f32_e32 v133, 1.0, v133
	v_cvt_pk_bf16_f32 v133, v135, v133
	global_store_dword v[226:227], v133, off offset:64
	s_mov_b64 s[4:5], 0x300
	v_lshl_add_u64 v[226:227], v[226:227], 0, s[4:5]
	v_add_f32_e32 v228, v51, v51
	v_mul_f32_e32 v228, 0x3fb8aa3b, v228
	v_exp_f32_e32 v228, v228
	s_nop 0
	v_add_f32_e32 v229, 1.0, v228
	v_div_scale_f32 v230, s[4:5], v229, v229, 2.0
	v_rcp_f32_e32 v231, v230
	v_div_scale_f32 v232, vcc, 2.0, v229, 2.0
	v_fma_f32 v131, -v230, v231, 1.0
	v_fmac_f32_e32 v231, v131, v231
	v_mul_f32_e32 v233, v232, v231
	v_fma_f32 v131, -v230, v233, v232
	v_fmac_f32_e32 v233, v131, v231
	v_fma_f32 v230, -v230, v233, v232
	v_div_fmas_f32 v230, v230, v231, v233
	v_div_fixup_f32 v135, v230, v229, 2.0
	v_sub_f32_e32 v135, 1.0, v135
	v_add_f32_e32 v228, v55, v55
	v_mul_f32_e32 v228, 0x3fb8aa3b, v228
	v_exp_f32_e32 v228, v228
	s_nop 0
	v_add_f32_e32 v229, 1.0, v228
	v_div_scale_f32 v230, s[4:5], v229, v229, 2.0
	v_rcp_f32_e32 v231, v230
	v_div_scale_f32 v232, vcc, 2.0, v229, 2.0
	v_fma_f32 v131, -v230, v231, 1.0
	v_fmac_f32_e32 v231, v131, v231
	v_mul_f32_e32 v233, v232, v231
	v_fma_f32 v131, -v230, v233, v232
	v_fmac_f32_e32 v233, v131, v231
	v_fma_f32 v230, -v230, v233, v232
	v_div_fmas_f32 v230, v230, v231, v233
	v_div_fixup_f32 v133, v230, v229, 2.0
	v_sub_f32_e32 v133, 1.0, v133
	v_cvt_pk_bf16_f32 v133, v135, v133
	global_store_dword v[226:227], v133, off
	v_add_f32_e32 v228, v59, v59
	v_mul_f32_e32 v228, 0x3fb8aa3b, v228
	v_exp_f32_e32 v228, v228
	s_nop 0
	v_add_f32_e32 v229, 1.0, v228
	v_div_scale_f32 v230, s[4:5], v229, v229, 2.0
	v_rcp_f32_e32 v231, v230
	v_div_scale_f32 v232, vcc, 2.0, v229, 2.0
	v_fma_f32 v131, -v230, v231, 1.0
	v_fmac_f32_e32 v231, v131, v231
	v_mul_f32_e32 v233, v232, v231
	v_fma_f32 v131, -v230, v233, v232
	v_fmac_f32_e32 v233, v131, v231
	v_fma_f32 v230, -v230, v233, v232
	v_div_fmas_f32 v230, v230, v231, v233
	v_div_fixup_f32 v135, v230, v229, 2.0
	v_sub_f32_e32 v135, 1.0, v135
	v_add_f32_e32 v228, v63, v63
	v_mul_f32_e32 v228, 0x3fb8aa3b, v228
	v_exp_f32_e32 v228, v228
	s_nop 0
	v_add_f32_e32 v229, 1.0, v228
	v_div_scale_f32 v230, s[4:5], v229, v229, 2.0
	v_rcp_f32_e32 v231, v230
	v_div_scale_f32 v232, vcc, 2.0, v229, 2.0
	v_fma_f32 v131, -v230, v231, 1.0
	v_fmac_f32_e32 v231, v131, v231
	v_mul_f32_e32 v233, v232, v231
	v_fma_f32 v131, -v230, v233, v232
	v_fmac_f32_e32 v233, v131, v231
	v_fma_f32 v230, -v230, v233, v232
	v_div_fmas_f32 v230, v230, v231, v233
	v_div_fixup_f32 v133, v230, v229, 2.0
	v_sub_f32_e32 v133, 1.0, v133
	v_cvt_pk_bf16_f32 v133, v135, v133
	global_store_dword v[226:227], v133, off offset:64
	s_mov_b64 s[4:5], 0x2700
	v_lshl_add_u64 v[226:227], v[226:227], 0, s[4:5]
	v_add_f32_e32 v228, v64, v64
	v_mul_f32_e32 v228, 0x3fb8aa3b, v228
	v_exp_f32_e32 v228, v228
	s_nop 0
	v_add_f32_e32 v229, 1.0, v228
	v_div_scale_f32 v230, s[4:5], v229, v229, 2.0
	v_rcp_f32_e32 v231, v230
	v_div_scale_f32 v232, vcc, 2.0, v229, 2.0
	v_fma_f32 v131, -v230, v231, 1.0
	v_fmac_f32_e32 v231, v131, v231
	v_mul_f32_e32 v233, v232, v231
	v_fma_f32 v131, -v230, v233, v232
	v_fmac_f32_e32 v233, v131, v231
	v_fma_f32 v230, -v230, v233, v232
	v_div_fmas_f32 v230, v230, v231, v233
	v_div_fixup_f32 v135, v230, v229, 2.0
	v_sub_f32_e32 v135, 1.0, v135
	v_add_f32_e32 v228, v68, v68
	v_mul_f32_e32 v228, 0x3fb8aa3b, v228
	v_exp_f32_e32 v228, v228
	s_nop 0
	v_add_f32_e32 v229, 1.0, v228
	v_div_scale_f32 v230, s[4:5], v229, v229, 2.0
	v_rcp_f32_e32 v231, v230
	v_div_scale_f32 v232, vcc, 2.0, v229, 2.0
	v_fma_f32 v131, -v230, v231, 1.0
	v_fmac_f32_e32 v231, v131, v231
	v_mul_f32_e32 v233, v232, v231
	v_fma_f32 v131, -v230, v233, v232
	v_fmac_f32_e32 v233, v131, v231
	v_fma_f32 v230, -v230, v233, v232
	v_div_fmas_f32 v230, v230, v231, v233
	v_div_fixup_f32 v133, v230, v229, 2.0
	v_sub_f32_e32 v133, 1.0, v133
	v_cvt_pk_bf16_f32 v133, v135, v133
	global_store_dword v[226:227], v133, off
	v_add_f32_e32 v228, v72, v72
	v_mul_f32_e32 v228, 0x3fb8aa3b, v228
	v_exp_f32_e32 v228, v228
	s_nop 0
	v_add_f32_e32 v229, 1.0, v228
	v_div_scale_f32 v230, s[4:5], v229, v229, 2.0
	v_rcp_f32_e32 v231, v230
	v_div_scale_f32 v232, vcc, 2.0, v229, 2.0
	v_fma_f32 v131, -v230, v231, 1.0
	v_fmac_f32_e32 v231, v131, v231
	v_mul_f32_e32 v233, v232, v231
	v_fma_f32 v131, -v230, v233, v232
	v_fmac_f32_e32 v233, v131, v231
	v_fma_f32 v230, -v230, v233, v232
	v_div_fmas_f32 v230, v230, v231, v233
	v_div_fixup_f32 v135, v230, v229, 2.0
	v_sub_f32_e32 v135, 1.0, v135
	v_add_f32_e32 v228, v76, v76
	v_mul_f32_e32 v228, 0x3fb8aa3b, v228
	v_exp_f32_e32 v228, v228
	s_nop 0
	v_add_f32_e32 v229, 1.0, v228
	v_div_scale_f32 v230, s[4:5], v229, v229, 2.0
	v_rcp_f32_e32 v231, v230
	v_div_scale_f32 v232, vcc, 2.0, v229, 2.0
	v_fma_f32 v131, -v230, v231, 1.0
	v_fmac_f32_e32 v231, v131, v231
	v_mul_f32_e32 v233, v232, v231
	v_fma_f32 v131, -v230, v233, v232
	v_fmac_f32_e32 v233, v131, v231
	v_fma_f32 v230, -v230, v233, v232
	v_div_fmas_f32 v230, v230, v231, v233
	v_div_fixup_f32 v133, v230, v229, 2.0
	v_sub_f32_e32 v133, 1.0, v133
	v_cvt_pk_bf16_f32 v133, v135, v133
	global_store_dword v[226:227], v133, off offset:64
	s_mov_b64 s[4:5], 0x300
	v_lshl_add_u64 v[226:227], v[226:227], 0, s[4:5]
	v_add_f32_e32 v228, v65, v65
	v_mul_f32_e32 v228, 0x3fb8aa3b, v228
	v_exp_f32_e32 v228, v228
	s_nop 0
	v_add_f32_e32 v229, 1.0, v228
	v_div_scale_f32 v230, s[4:5], v229, v229, 2.0
	v_rcp_f32_e32 v231, v230
	v_div_scale_f32 v232, vcc, 2.0, v229, 2.0
	v_fma_f32 v131, -v230, v231, 1.0
	v_fmac_f32_e32 v231, v131, v231
	v_mul_f32_e32 v233, v232, v231
	v_fma_f32 v131, -v230, v233, v232
	v_fmac_f32_e32 v233, v131, v231
	v_fma_f32 v230, -v230, v233, v232
	v_div_fmas_f32 v230, v230, v231, v233
	v_div_fixup_f32 v135, v230, v229, 2.0
	v_sub_f32_e32 v135, 1.0, v135
	v_add_f32_e32 v228, v69, v69
	v_mul_f32_e32 v228, 0x3fb8aa3b, v228
	v_exp_f32_e32 v228, v228
	s_nop 0
	v_add_f32_e32 v229, 1.0, v228
	v_div_scale_f32 v230, s[4:5], v229, v229, 2.0
	v_rcp_f32_e32 v231, v230
	v_div_scale_f32 v232, vcc, 2.0, v229, 2.0
	v_fma_f32 v131, -v230, v231, 1.0
	v_fmac_f32_e32 v231, v131, v231
	v_mul_f32_e32 v233, v232, v231
	v_fma_f32 v131, -v230, v233, v232
	v_fmac_f32_e32 v233, v131, v231
	v_fma_f32 v230, -v230, v233, v232
	v_div_fmas_f32 v230, v230, v231, v233
	v_div_fixup_f32 v133, v230, v229, 2.0
	v_sub_f32_e32 v133, 1.0, v133
	v_cvt_pk_bf16_f32 v133, v135, v133
	global_store_dword v[226:227], v133, off
	v_add_f32_e32 v228, v73, v73
	v_mul_f32_e32 v228, 0x3fb8aa3b, v228
	v_exp_f32_e32 v228, v228
	s_nop 0
	v_add_f32_e32 v229, 1.0, v228
	v_div_scale_f32 v230, s[4:5], v229, v229, 2.0
	v_rcp_f32_e32 v231, v230
	v_div_scale_f32 v232, vcc, 2.0, v229, 2.0
	v_fma_f32 v131, -v230, v231, 1.0
	v_fmac_f32_e32 v231, v131, v231
	v_mul_f32_e32 v233, v232, v231
	v_fma_f32 v131, -v230, v233, v232
	v_fmac_f32_e32 v233, v131, v231
	v_fma_f32 v230, -v230, v233, v232
	v_div_fmas_f32 v230, v230, v231, v233
	v_div_fixup_f32 v135, v230, v229, 2.0
	v_sub_f32_e32 v135, 1.0, v135
	v_add_f32_e32 v228, v77, v77
	v_mul_f32_e32 v228, 0x3fb8aa3b, v228
	v_exp_f32_e32 v228, v228
	s_nop 0
	v_add_f32_e32 v229, 1.0, v228
	v_div_scale_f32 v230, s[4:5], v229, v229, 2.0
	v_rcp_f32_e32 v231, v230
	v_div_scale_f32 v232, vcc, 2.0, v229, 2.0
	v_fma_f32 v131, -v230, v231, 1.0
	v_fmac_f32_e32 v231, v131, v231
	v_mul_f32_e32 v233, v232, v231
	v_fma_f32 v131, -v230, v233, v232
	v_fmac_f32_e32 v233, v131, v231
	v_fma_f32 v230, -v230, v233, v232
	v_div_fmas_f32 v230, v230, v231, v233
	v_div_fixup_f32 v133, v230, v229, 2.0
	v_sub_f32_e32 v133, 1.0, v133
	v_cvt_pk_bf16_f32 v133, v135, v133
	global_store_dword v[226:227], v133, off offset:64
	s_mov_b64 s[4:5], 0x300
	v_lshl_add_u64 v[226:227], v[226:227], 0, s[4:5]
	v_add_f32_e32 v228, v66, v66
	v_mul_f32_e32 v228, 0x3fb8aa3b, v228
	v_exp_f32_e32 v228, v228
	s_nop 0
	v_add_f32_e32 v229, 1.0, v228
	v_div_scale_f32 v230, s[4:5], v229, v229, 2.0
	v_rcp_f32_e32 v231, v230
	v_div_scale_f32 v232, vcc, 2.0, v229, 2.0
	v_fma_f32 v131, -v230, v231, 1.0
	v_fmac_f32_e32 v231, v131, v231
	v_mul_f32_e32 v233, v232, v231
	v_fma_f32 v131, -v230, v233, v232
	v_fmac_f32_e32 v233, v131, v231
	v_fma_f32 v230, -v230, v233, v232
	v_div_fmas_f32 v230, v230, v231, v233
	v_div_fixup_f32 v135, v230, v229, 2.0
	v_sub_f32_e32 v135, 1.0, v135
	v_add_f32_e32 v228, v70, v70
	v_mul_f32_e32 v228, 0x3fb8aa3b, v228
	v_exp_f32_e32 v228, v228
	s_nop 0
	v_add_f32_e32 v229, 1.0, v228
	v_div_scale_f32 v230, s[4:5], v229, v229, 2.0
	v_rcp_f32_e32 v231, v230
	v_div_scale_f32 v232, vcc, 2.0, v229, 2.0
	v_fma_f32 v131, -v230, v231, 1.0
	v_fmac_f32_e32 v231, v131, v231
	v_mul_f32_e32 v233, v232, v231
	v_fma_f32 v131, -v230, v233, v232
	v_fmac_f32_e32 v233, v131, v231
	v_fma_f32 v230, -v230, v233, v232
	v_div_fmas_f32 v230, v230, v231, v233
	v_div_fixup_f32 v133, v230, v229, 2.0
	v_sub_f32_e32 v133, 1.0, v133
	v_cvt_pk_bf16_f32 v133, v135, v133
	global_store_dword v[226:227], v133, off
	v_add_f32_e32 v228, v74, v74
	v_mul_f32_e32 v228, 0x3fb8aa3b, v228
	v_exp_f32_e32 v228, v228
	s_nop 0
	v_add_f32_e32 v229, 1.0, v228
	v_div_scale_f32 v230, s[4:5], v229, v229, 2.0
	v_rcp_f32_e32 v231, v230
	v_div_scale_f32 v232, vcc, 2.0, v229, 2.0
	v_fma_f32 v131, -v230, v231, 1.0
	v_fmac_f32_e32 v231, v131, v231
	v_mul_f32_e32 v233, v232, v231
	v_fma_f32 v131, -v230, v233, v232
	v_fmac_f32_e32 v233, v131, v231
	v_fma_f32 v230, -v230, v233, v232
	v_div_fmas_f32 v230, v230, v231, v233
	v_div_fixup_f32 v135, v230, v229, 2.0
	v_sub_f32_e32 v135, 1.0, v135
	v_add_f32_e32 v228, v78, v78
	v_mul_f32_e32 v228, 0x3fb8aa3b, v228
	v_exp_f32_e32 v228, v228
	s_nop 0
	v_add_f32_e32 v229, 1.0, v228
	v_div_scale_f32 v230, s[4:5], v229, v229, 2.0
	v_rcp_f32_e32 v231, v230
	v_div_scale_f32 v232, vcc, 2.0, v229, 2.0
	v_fma_f32 v131, -v230, v231, 1.0
	v_fmac_f32_e32 v231, v131, v231
	v_mul_f32_e32 v233, v232, v231
	v_fma_f32 v131, -v230, v233, v232
	v_fmac_f32_e32 v233, v131, v231
	v_fma_f32 v230, -v230, v233, v232
	v_div_fmas_f32 v230, v230, v231, v233
	v_div_fixup_f32 v133, v230, v229, 2.0
	v_sub_f32_e32 v133, 1.0, v133
	v_cvt_pk_bf16_f32 v133, v135, v133
	global_store_dword v[226:227], v133, off offset:64
	s_mov_b64 s[4:5], 0x300
	v_lshl_add_u64 v[226:227], v[226:227], 0, s[4:5]
	v_add_f32_e32 v228, v67, v67
	v_mul_f32_e32 v228, 0x3fb8aa3b, v228
	v_exp_f32_e32 v228, v228
	s_nop 0
	v_add_f32_e32 v229, 1.0, v228
	v_div_scale_f32 v230, s[4:5], v229, v229, 2.0
	v_rcp_f32_e32 v231, v230
	v_div_scale_f32 v232, vcc, 2.0, v229, 2.0
	v_fma_f32 v131, -v230, v231, 1.0
	v_fmac_f32_e32 v231, v131, v231
	v_mul_f32_e32 v233, v232, v231
	v_fma_f32 v131, -v230, v233, v232
	v_fmac_f32_e32 v233, v131, v231
	v_fma_f32 v230, -v230, v233, v232
	v_div_fmas_f32 v230, v230, v231, v233
	v_div_fixup_f32 v135, v230, v229, 2.0
	v_sub_f32_e32 v135, 1.0, v135
	v_add_f32_e32 v228, v71, v71
	v_mul_f32_e32 v228, 0x3fb8aa3b, v228
	v_exp_f32_e32 v228, v228
	s_nop 0
	v_add_f32_e32 v229, 1.0, v228
	v_div_scale_f32 v230, s[4:5], v229, v229, 2.0
	v_rcp_f32_e32 v231, v230
	v_div_scale_f32 v232, vcc, 2.0, v229, 2.0
	v_fma_f32 v131, -v230, v231, 1.0
	v_fmac_f32_e32 v231, v131, v231
	v_mul_f32_e32 v233, v232, v231
	v_fma_f32 v131, -v230, v233, v232
	v_fmac_f32_e32 v233, v131, v231
	v_fma_f32 v230, -v230, v233, v232
	v_div_fmas_f32 v230, v230, v231, v233
	v_div_fixup_f32 v133, v230, v229, 2.0
	v_sub_f32_e32 v133, 1.0, v133
	v_cvt_pk_bf16_f32 v133, v135, v133
	global_store_dword v[226:227], v133, off
	v_add_f32_e32 v228, v75, v75
	v_mul_f32_e32 v228, 0x3fb8aa3b, v228
	v_exp_f32_e32 v228, v228
	s_nop 0
	v_add_f32_e32 v229, 1.0, v228
	v_div_scale_f32 v230, s[4:5], v229, v229, 2.0
	v_rcp_f32_e32 v231, v230
	v_div_scale_f32 v232, vcc, 2.0, v229, 2.0
	v_fma_f32 v131, -v230, v231, 1.0
	v_fmac_f32_e32 v231, v131, v231
	v_mul_f32_e32 v233, v232, v231
	v_fma_f32 v131, -v230, v233, v232
	v_fmac_f32_e32 v233, v131, v231
	v_fma_f32 v230, -v230, v233, v232
	v_div_fmas_f32 v230, v230, v231, v233
	v_div_fixup_f32 v135, v230, v229, 2.0
	v_sub_f32_e32 v135, 1.0, v135
	v_add_f32_e32 v228, v79, v79
	v_mul_f32_e32 v228, 0x3fb8aa3b, v228
	v_exp_f32_e32 v228, v228
	s_nop 0
	v_add_f32_e32 v229, 1.0, v228
	v_div_scale_f32 v230, s[4:5], v229, v229, 2.0
	v_rcp_f32_e32 v231, v230
	v_div_scale_f32 v232, vcc, 2.0, v229, 2.0
	v_fma_f32 v131, -v230, v231, 1.0
	v_fmac_f32_e32 v231, v131, v231
	v_mul_f32_e32 v233, v232, v231
	v_fma_f32 v131, -v230, v233, v232
	v_fmac_f32_e32 v233, v131, v231
	v_fma_f32 v230, -v230, v233, v232
	v_div_fmas_f32 v230, v230, v231, v233
	v_div_fixup_f32 v133, v230, v229, 2.0
	v_sub_f32_e32 v133, 1.0, v133
	v_cvt_pk_bf16_f32 v133, v135, v133
	global_store_dword v[226:227], v133, off offset:64
	s_mov_b64 s[4:5], 0x2700
	v_lshl_add_u64 v[226:227], v[226:227], 0, s[4:5]
	v_add_f32_e32 v228, v80, v80
	v_mul_f32_e32 v228, 0x3fb8aa3b, v228
	v_exp_f32_e32 v228, v228
	s_nop 0
	v_add_f32_e32 v229, 1.0, v228
	v_div_scale_f32 v230, s[4:5], v229, v229, 2.0
	v_rcp_f32_e32 v231, v230
	v_div_scale_f32 v232, vcc, 2.0, v229, 2.0
	v_fma_f32 v131, -v230, v231, 1.0
	v_fmac_f32_e32 v231, v131, v231
	v_mul_f32_e32 v233, v232, v231
	v_fma_f32 v131, -v230, v233, v232
	v_fmac_f32_e32 v233, v131, v231
	v_fma_f32 v230, -v230, v233, v232
	v_div_fmas_f32 v230, v230, v231, v233
	v_div_fixup_f32 v135, v230, v229, 2.0
	v_sub_f32_e32 v135, 1.0, v135
	v_add_f32_e32 v228, v84, v84
	v_mul_f32_e32 v228, 0x3fb8aa3b, v228
	v_exp_f32_e32 v228, v228
	s_nop 0
	v_add_f32_e32 v229, 1.0, v228
	v_div_scale_f32 v230, s[4:5], v229, v229, 2.0
	v_rcp_f32_e32 v231, v230
	v_div_scale_f32 v232, vcc, 2.0, v229, 2.0
	v_fma_f32 v131, -v230, v231, 1.0
	v_fmac_f32_e32 v231, v131, v231
	v_mul_f32_e32 v233, v232, v231
	v_fma_f32 v131, -v230, v233, v232
	v_fmac_f32_e32 v233, v131, v231
	v_fma_f32 v230, -v230, v233, v232
	v_div_fmas_f32 v230, v230, v231, v233
	v_div_fixup_f32 v133, v230, v229, 2.0
	v_sub_f32_e32 v133, 1.0, v133
	v_cvt_pk_bf16_f32 v133, v135, v133
	global_store_dword v[226:227], v133, off
	v_add_f32_e32 v228, v88, v88
	v_mul_f32_e32 v228, 0x3fb8aa3b, v228
	v_exp_f32_e32 v228, v228
	s_nop 0
	v_add_f32_e32 v229, 1.0, v228
	v_div_scale_f32 v230, s[4:5], v229, v229, 2.0
	v_rcp_f32_e32 v231, v230
	v_div_scale_f32 v232, vcc, 2.0, v229, 2.0
	v_fma_f32 v131, -v230, v231, 1.0
	v_fmac_f32_e32 v231, v131, v231
	v_mul_f32_e32 v233, v232, v231
	v_fma_f32 v131, -v230, v233, v232
	v_fmac_f32_e32 v233, v131, v231
	v_fma_f32 v230, -v230, v233, v232
	v_div_fmas_f32 v230, v230, v231, v233
	v_div_fixup_f32 v135, v230, v229, 2.0
	v_sub_f32_e32 v135, 1.0, v135
	v_add_f32_e32 v228, v92, v92
	v_mul_f32_e32 v228, 0x3fb8aa3b, v228
	v_exp_f32_e32 v228, v228
	s_nop 0
	v_add_f32_e32 v229, 1.0, v228
	v_div_scale_f32 v230, s[4:5], v229, v229, 2.0
	v_rcp_f32_e32 v231, v230
	v_div_scale_f32 v232, vcc, 2.0, v229, 2.0
	v_fma_f32 v131, -v230, v231, 1.0
	v_fmac_f32_e32 v231, v131, v231
	v_mul_f32_e32 v233, v232, v231
	v_fma_f32 v131, -v230, v233, v232
	v_fmac_f32_e32 v233, v131, v231
	v_fma_f32 v230, -v230, v233, v232
	v_div_fmas_f32 v230, v230, v231, v233
	v_div_fixup_f32 v133, v230, v229, 2.0
	v_sub_f32_e32 v133, 1.0, v133
	v_cvt_pk_bf16_f32 v133, v135, v133
	global_store_dword v[226:227], v133, off offset:64
	s_mov_b64 s[4:5], 0x300
	v_lshl_add_u64 v[226:227], v[226:227], 0, s[4:5]
	v_add_f32_e32 v228, v81, v81
	v_mul_f32_e32 v228, 0x3fb8aa3b, v228
	v_exp_f32_e32 v228, v228
	s_nop 0
	v_add_f32_e32 v229, 1.0, v228
	v_div_scale_f32 v230, s[4:5], v229, v229, 2.0
	v_rcp_f32_e32 v231, v230
	v_div_scale_f32 v232, vcc, 2.0, v229, 2.0
	v_fma_f32 v131, -v230, v231, 1.0
	v_fmac_f32_e32 v231, v131, v231
	v_mul_f32_e32 v233, v232, v231
	v_fma_f32 v131, -v230, v233, v232
	v_fmac_f32_e32 v233, v131, v231
	v_fma_f32 v230, -v230, v233, v232
	v_div_fmas_f32 v230, v230, v231, v233
	v_div_fixup_f32 v135, v230, v229, 2.0
	v_sub_f32_e32 v135, 1.0, v135
	v_add_f32_e32 v228, v85, v85
	v_mul_f32_e32 v228, 0x3fb8aa3b, v228
	v_exp_f32_e32 v228, v228
	s_nop 0
	v_add_f32_e32 v229, 1.0, v228
	v_div_scale_f32 v230, s[4:5], v229, v229, 2.0
	v_rcp_f32_e32 v231, v230
	v_div_scale_f32 v232, vcc, 2.0, v229, 2.0
	v_fma_f32 v131, -v230, v231, 1.0
	v_fmac_f32_e32 v231, v131, v231
	v_mul_f32_e32 v233, v232, v231
	v_fma_f32 v131, -v230, v233, v232
	v_fmac_f32_e32 v233, v131, v231
	v_fma_f32 v230, -v230, v233, v232
	v_div_fmas_f32 v230, v230, v231, v233
	v_div_fixup_f32 v133, v230, v229, 2.0
	v_sub_f32_e32 v133, 1.0, v133
	v_cvt_pk_bf16_f32 v133, v135, v133
	global_store_dword v[226:227], v133, off
	v_add_f32_e32 v228, v89, v89
	v_mul_f32_e32 v228, 0x3fb8aa3b, v228
	v_exp_f32_e32 v228, v228
	s_nop 0
	v_add_f32_e32 v229, 1.0, v228
	v_div_scale_f32 v230, s[4:5], v229, v229, 2.0
	v_rcp_f32_e32 v231, v230
	v_div_scale_f32 v232, vcc, 2.0, v229, 2.0
	v_fma_f32 v131, -v230, v231, 1.0
	v_fmac_f32_e32 v231, v131, v231
	v_mul_f32_e32 v233, v232, v231
	v_fma_f32 v131, -v230, v233, v232
	v_fmac_f32_e32 v233, v131, v231
	v_fma_f32 v230, -v230, v233, v232
	v_div_fmas_f32 v230, v230, v231, v233
	v_div_fixup_f32 v135, v230, v229, 2.0
	v_sub_f32_e32 v135, 1.0, v135
	v_add_f32_e32 v228, v93, v93
	v_mul_f32_e32 v228, 0x3fb8aa3b, v228
	v_exp_f32_e32 v228, v228
	s_nop 0
	v_add_f32_e32 v229, 1.0, v228
	v_div_scale_f32 v230, s[4:5], v229, v229, 2.0
	v_rcp_f32_e32 v231, v230
	v_div_scale_f32 v232, vcc, 2.0, v229, 2.0
	v_fma_f32 v131, -v230, v231, 1.0
	v_fmac_f32_e32 v231, v131, v231
	v_mul_f32_e32 v233, v232, v231
	v_fma_f32 v131, -v230, v233, v232
	v_fmac_f32_e32 v233, v131, v231
	v_fma_f32 v230, -v230, v233, v232
	v_div_fmas_f32 v230, v230, v231, v233
	v_div_fixup_f32 v133, v230, v229, 2.0
	v_sub_f32_e32 v133, 1.0, v133
	v_cvt_pk_bf16_f32 v133, v135, v133
	global_store_dword v[226:227], v133, off offset:64
	s_mov_b64 s[4:5], 0x300
	v_lshl_add_u64 v[226:227], v[226:227], 0, s[4:5]
	v_add_f32_e32 v228, v82, v82
	v_mul_f32_e32 v228, 0x3fb8aa3b, v228
	v_exp_f32_e32 v228, v228
	s_nop 0
	v_add_f32_e32 v229, 1.0, v228
	v_div_scale_f32 v230, s[4:5], v229, v229, 2.0
	v_rcp_f32_e32 v231, v230
	v_div_scale_f32 v232, vcc, 2.0, v229, 2.0
	v_fma_f32 v131, -v230, v231, 1.0
	v_fmac_f32_e32 v231, v131, v231
	v_mul_f32_e32 v233, v232, v231
	v_fma_f32 v131, -v230, v233, v232
	v_fmac_f32_e32 v233, v131, v231
	v_fma_f32 v230, -v230, v233, v232
	v_div_fmas_f32 v230, v230, v231, v233
	v_div_fixup_f32 v135, v230, v229, 2.0
	v_sub_f32_e32 v135, 1.0, v135
	v_add_f32_e32 v228, v86, v86
	v_mul_f32_e32 v228, 0x3fb8aa3b, v228
	v_exp_f32_e32 v228, v228
	s_nop 0
	v_add_f32_e32 v229, 1.0, v228
	v_div_scale_f32 v230, s[4:5], v229, v229, 2.0
	v_rcp_f32_e32 v231, v230
	v_div_scale_f32 v232, vcc, 2.0, v229, 2.0
	v_fma_f32 v131, -v230, v231, 1.0
	v_fmac_f32_e32 v231, v131, v231
	v_mul_f32_e32 v233, v232, v231
	v_fma_f32 v131, -v230, v233, v232
	v_fmac_f32_e32 v233, v131, v231
	v_fma_f32 v230, -v230, v233, v232
	v_div_fmas_f32 v230, v230, v231, v233
	v_div_fixup_f32 v133, v230, v229, 2.0
	v_sub_f32_e32 v133, 1.0, v133
	v_cvt_pk_bf16_f32 v133, v135, v133
	global_store_dword v[226:227], v133, off
	v_add_f32_e32 v228, v90, v90
	v_mul_f32_e32 v228, 0x3fb8aa3b, v228
	v_exp_f32_e32 v228, v228
	s_nop 0
	v_add_f32_e32 v229, 1.0, v228
	v_div_scale_f32 v230, s[4:5], v229, v229, 2.0
	v_rcp_f32_e32 v231, v230
	v_div_scale_f32 v232, vcc, 2.0, v229, 2.0
	v_fma_f32 v131, -v230, v231, 1.0
	v_fmac_f32_e32 v231, v131, v231
	v_mul_f32_e32 v233, v232, v231
	v_fma_f32 v131, -v230, v233, v232
	v_fmac_f32_e32 v233, v131, v231
	v_fma_f32 v230, -v230, v233, v232
	v_div_fmas_f32 v230, v230, v231, v233
	v_div_fixup_f32 v135, v230, v229, 2.0
	v_sub_f32_e32 v135, 1.0, v135
	v_add_f32_e32 v228, v94, v94
	v_mul_f32_e32 v228, 0x3fb8aa3b, v228
	v_exp_f32_e32 v228, v228
	s_nop 0
	v_add_f32_e32 v229, 1.0, v228
	v_div_scale_f32 v230, s[4:5], v229, v229, 2.0
	v_rcp_f32_e32 v231, v230
	v_div_scale_f32 v232, vcc, 2.0, v229, 2.0
	v_fma_f32 v131, -v230, v231, 1.0
	v_fmac_f32_e32 v231, v131, v231
	v_mul_f32_e32 v233, v232, v231
	v_fma_f32 v131, -v230, v233, v232
	v_fmac_f32_e32 v233, v131, v231
	v_fma_f32 v230, -v230, v233, v232
	v_div_fmas_f32 v230, v230, v231, v233
	v_div_fixup_f32 v133, v230, v229, 2.0
	v_sub_f32_e32 v133, 1.0, v133
	v_cvt_pk_bf16_f32 v133, v135, v133
	global_store_dword v[226:227], v133, off offset:64
	s_mov_b64 s[4:5], 0x300
	v_lshl_add_u64 v[226:227], v[226:227], 0, s[4:5]
	v_add_f32_e32 v228, v83, v83
	v_mul_f32_e32 v228, 0x3fb8aa3b, v228
	v_exp_f32_e32 v228, v228
	s_nop 0
	v_add_f32_e32 v229, 1.0, v228
	v_div_scale_f32 v230, s[4:5], v229, v229, 2.0
	v_rcp_f32_e32 v231, v230
	v_div_scale_f32 v232, vcc, 2.0, v229, 2.0
	v_fma_f32 v131, -v230, v231, 1.0
	v_fmac_f32_e32 v231, v131, v231
	v_mul_f32_e32 v233, v232, v231
	v_fma_f32 v131, -v230, v233, v232
	v_fmac_f32_e32 v233, v131, v231
	v_fma_f32 v230, -v230, v233, v232
	v_div_fmas_f32 v230, v230, v231, v233
	v_div_fixup_f32 v135, v230, v229, 2.0
	v_sub_f32_e32 v135, 1.0, v135
	v_add_f32_e32 v228, v87, v87
	v_mul_f32_e32 v228, 0x3fb8aa3b, v228
	v_exp_f32_e32 v228, v228
	s_nop 0
	v_add_f32_e32 v229, 1.0, v228
	v_div_scale_f32 v230, s[4:5], v229, v229, 2.0
	v_rcp_f32_e32 v231, v230
	v_div_scale_f32 v232, vcc, 2.0, v229, 2.0
	v_fma_f32 v131, -v230, v231, 1.0
	v_fmac_f32_e32 v231, v131, v231
	v_mul_f32_e32 v233, v232, v231
	v_fma_f32 v131, -v230, v233, v232
	v_fmac_f32_e32 v233, v131, v231
	v_fma_f32 v230, -v230, v233, v232
	v_div_fmas_f32 v230, v230, v231, v233
	v_div_fixup_f32 v133, v230, v229, 2.0
	v_sub_f32_e32 v133, 1.0, v133
	v_cvt_pk_bf16_f32 v133, v135, v133
	global_store_dword v[226:227], v133, off
	v_add_f32_e32 v228, v91, v91
	v_mul_f32_e32 v228, 0x3fb8aa3b, v228
	v_exp_f32_e32 v228, v228
	s_nop 0
	v_add_f32_e32 v229, 1.0, v228
	v_div_scale_f32 v230, s[4:5], v229, v229, 2.0
	v_rcp_f32_e32 v231, v230
	v_div_scale_f32 v232, vcc, 2.0, v229, 2.0
	v_fma_f32 v131, -v230, v231, 1.0
	v_fmac_f32_e32 v231, v131, v231
	v_mul_f32_e32 v233, v232, v231
	v_fma_f32 v131, -v230, v233, v232
	v_fmac_f32_e32 v233, v131, v231
	v_fma_f32 v230, -v230, v233, v232
	v_div_fmas_f32 v230, v230, v231, v233
	v_div_fixup_f32 v135, v230, v229, 2.0
	v_sub_f32_e32 v135, 1.0, v135
	v_add_f32_e32 v228, v95, v95
	v_mul_f32_e32 v228, 0x3fb8aa3b, v228
	v_exp_f32_e32 v228, v228
	s_nop 0
	v_add_f32_e32 v229, 1.0, v228
	v_div_scale_f32 v230, s[4:5], v229, v229, 2.0
	v_rcp_f32_e32 v231, v230
	v_div_scale_f32 v232, vcc, 2.0, v229, 2.0
	v_fma_f32 v131, -v230, v231, 1.0
	v_fmac_f32_e32 v231, v131, v231
	v_mul_f32_e32 v233, v232, v231
	v_fma_f32 v131, -v230, v233, v232
	v_fmac_f32_e32 v233, v131, v231
	v_fma_f32 v230, -v230, v233, v232
	v_div_fmas_f32 v230, v230, v231, v233
	v_div_fixup_f32 v133, v230, v229, 2.0
	v_sub_f32_e32 v133, 1.0, v133
	v_cvt_pk_bf16_f32 v133, v135, v133
	global_store_dword v[226:227], v133, off offset:64
	s_mov_b64 s[4:5], 0x2700
	v_lshl_add_u64 v[226:227], v[226:227], 0, s[4:5]
	v_add_f32_e32 v228, v96, v96
	v_mul_f32_e32 v228, 0x3fb8aa3b, v228
	v_exp_f32_e32 v228, v228
	s_nop 0
	v_add_f32_e32 v229, 1.0, v228
	v_div_scale_f32 v230, s[4:5], v229, v229, 2.0
	v_rcp_f32_e32 v231, v230
	v_div_scale_f32 v232, vcc, 2.0, v229, 2.0
	v_fma_f32 v131, -v230, v231, 1.0
	v_fmac_f32_e32 v231, v131, v231
	v_mul_f32_e32 v233, v232, v231
	v_fma_f32 v131, -v230, v233, v232
	v_fmac_f32_e32 v233, v131, v231
	v_fma_f32 v230, -v230, v233, v232
	v_div_fmas_f32 v230, v230, v231, v233
	v_div_fixup_f32 v135, v230, v229, 2.0
	v_sub_f32_e32 v135, 1.0, v135
	v_add_f32_e32 v228, v100, v100
	v_mul_f32_e32 v228, 0x3fb8aa3b, v228
	v_exp_f32_e32 v228, v228
	s_nop 0
	v_add_f32_e32 v229, 1.0, v228
	v_div_scale_f32 v230, s[4:5], v229, v229, 2.0
	v_rcp_f32_e32 v231, v230
	v_div_scale_f32 v232, vcc, 2.0, v229, 2.0
	v_fma_f32 v131, -v230, v231, 1.0
	v_fmac_f32_e32 v231, v131, v231
	v_mul_f32_e32 v233, v232, v231
	v_fma_f32 v131, -v230, v233, v232
	v_fmac_f32_e32 v233, v131, v231
	v_fma_f32 v230, -v230, v233, v232
	v_div_fmas_f32 v230, v230, v231, v233
	v_div_fixup_f32 v133, v230, v229, 2.0
	v_sub_f32_e32 v133, 1.0, v133
	v_cvt_pk_bf16_f32 v133, v135, v133
	global_store_dword v[226:227], v133, off
	v_add_f32_e32 v228, v104, v104
	v_mul_f32_e32 v228, 0x3fb8aa3b, v228
	v_exp_f32_e32 v228, v228
	s_nop 0
	v_add_f32_e32 v229, 1.0, v228
	v_div_scale_f32 v230, s[4:5], v229, v229, 2.0
	v_rcp_f32_e32 v231, v230
	v_div_scale_f32 v232, vcc, 2.0, v229, 2.0
	v_fma_f32 v131, -v230, v231, 1.0
	v_fmac_f32_e32 v231, v131, v231
	v_mul_f32_e32 v233, v232, v231
	v_fma_f32 v131, -v230, v233, v232
	v_fmac_f32_e32 v233, v131, v231
	v_fma_f32 v230, -v230, v233, v232
	v_div_fmas_f32 v230, v230, v231, v233
	v_div_fixup_f32 v135, v230, v229, 2.0
	v_sub_f32_e32 v135, 1.0, v135
	v_add_f32_e32 v228, v108, v108
	v_mul_f32_e32 v228, 0x3fb8aa3b, v228
	v_exp_f32_e32 v228, v228
	s_nop 0
	v_add_f32_e32 v229, 1.0, v228
	v_div_scale_f32 v230, s[4:5], v229, v229, 2.0
	v_rcp_f32_e32 v231, v230
	v_div_scale_f32 v232, vcc, 2.0, v229, 2.0
	v_fma_f32 v131, -v230, v231, 1.0
	v_fmac_f32_e32 v231, v131, v231
	v_mul_f32_e32 v233, v232, v231
	v_fma_f32 v131, -v230, v233, v232
	v_fmac_f32_e32 v233, v131, v231
	v_fma_f32 v230, -v230, v233, v232
	v_div_fmas_f32 v230, v230, v231, v233
	v_div_fixup_f32 v133, v230, v229, 2.0
	v_sub_f32_e32 v133, 1.0, v133
	v_cvt_pk_bf16_f32 v133, v135, v133
	global_store_dword v[226:227], v133, off offset:64
	s_mov_b64 s[4:5], 0x300
	v_lshl_add_u64 v[226:227], v[226:227], 0, s[4:5]
	v_add_f32_e32 v228, v97, v97
	v_mul_f32_e32 v228, 0x3fb8aa3b, v228
	v_exp_f32_e32 v228, v228
	s_nop 0
	v_add_f32_e32 v229, 1.0, v228
	v_div_scale_f32 v230, s[4:5], v229, v229, 2.0
	v_rcp_f32_e32 v231, v230
	v_div_scale_f32 v232, vcc, 2.0, v229, 2.0
	v_fma_f32 v131, -v230, v231, 1.0
	v_fmac_f32_e32 v231, v131, v231
	v_mul_f32_e32 v233, v232, v231
	v_fma_f32 v131, -v230, v233, v232
	v_fmac_f32_e32 v233, v131, v231
	v_fma_f32 v230, -v230, v233, v232
	v_div_fmas_f32 v230, v230, v231, v233
	v_div_fixup_f32 v135, v230, v229, 2.0
	v_sub_f32_e32 v135, 1.0, v135
	v_add_f32_e32 v228, v101, v101
	v_mul_f32_e32 v228, 0x3fb8aa3b, v228
	v_exp_f32_e32 v228, v228
	s_nop 0
	v_add_f32_e32 v229, 1.0, v228
	v_div_scale_f32 v230, s[4:5], v229, v229, 2.0
	v_rcp_f32_e32 v231, v230
	v_div_scale_f32 v232, vcc, 2.0, v229, 2.0
	v_fma_f32 v131, -v230, v231, 1.0
	v_fmac_f32_e32 v231, v131, v231
	v_mul_f32_e32 v233, v232, v231
	v_fma_f32 v131, -v230, v233, v232
	v_fmac_f32_e32 v233, v131, v231
	v_fma_f32 v230, -v230, v233, v232
	v_div_fmas_f32 v230, v230, v231, v233
	v_div_fixup_f32 v133, v230, v229, 2.0
	v_sub_f32_e32 v133, 1.0, v133
	v_cvt_pk_bf16_f32 v133, v135, v133
	global_store_dword v[226:227], v133, off
	v_add_f32_e32 v228, v105, v105
	v_mul_f32_e32 v228, 0x3fb8aa3b, v228
	v_exp_f32_e32 v228, v228
	s_nop 0
	v_add_f32_e32 v229, 1.0, v228
	v_div_scale_f32 v230, s[4:5], v229, v229, 2.0
	v_rcp_f32_e32 v231, v230
	v_div_scale_f32 v232, vcc, 2.0, v229, 2.0
	v_fma_f32 v131, -v230, v231, 1.0
	v_fmac_f32_e32 v231, v131, v231
	v_mul_f32_e32 v233, v232, v231
	v_fma_f32 v131, -v230, v233, v232
	v_fmac_f32_e32 v233, v131, v231
	v_fma_f32 v230, -v230, v233, v232
	v_div_fmas_f32 v230, v230, v231, v233
	v_div_fixup_f32 v135, v230, v229, 2.0
	v_sub_f32_e32 v135, 1.0, v135
	v_add_f32_e32 v228, v109, v109
	v_mul_f32_e32 v228, 0x3fb8aa3b, v228
	v_exp_f32_e32 v228, v228
	s_nop 0
	v_add_f32_e32 v229, 1.0, v228
	v_div_scale_f32 v230, s[4:5], v229, v229, 2.0
	v_rcp_f32_e32 v231, v230
	v_div_scale_f32 v232, vcc, 2.0, v229, 2.0
	v_fma_f32 v131, -v230, v231, 1.0
	v_fmac_f32_e32 v231, v131, v231
	v_mul_f32_e32 v233, v232, v231
	v_fma_f32 v131, -v230, v233, v232
	v_fmac_f32_e32 v233, v131, v231
	v_fma_f32 v230, -v230, v233, v232
	v_div_fmas_f32 v230, v230, v231, v233
	v_div_fixup_f32 v133, v230, v229, 2.0
	v_sub_f32_e32 v133, 1.0, v133
	v_cvt_pk_bf16_f32 v133, v135, v133
	global_store_dword v[226:227], v133, off offset:64
	s_mov_b64 s[4:5], 0x300
	v_lshl_add_u64 v[226:227], v[226:227], 0, s[4:5]
	v_add_f32_e32 v228, v98, v98
	v_mul_f32_e32 v228, 0x3fb8aa3b, v228
	v_exp_f32_e32 v228, v228
	s_nop 0
	v_add_f32_e32 v229, 1.0, v228
	v_div_scale_f32 v230, s[4:5], v229, v229, 2.0
	v_rcp_f32_e32 v231, v230
	v_div_scale_f32 v232, vcc, 2.0, v229, 2.0
	v_fma_f32 v131, -v230, v231, 1.0
	v_fmac_f32_e32 v231, v131, v231
	v_mul_f32_e32 v233, v232, v231
	v_fma_f32 v131, -v230, v233, v232
	v_fmac_f32_e32 v233, v131, v231
	v_fma_f32 v230, -v230, v233, v232
	v_div_fmas_f32 v230, v230, v231, v233
	v_div_fixup_f32 v135, v230, v229, 2.0
	v_sub_f32_e32 v135, 1.0, v135
	v_add_f32_e32 v228, v102, v102
	v_mul_f32_e32 v228, 0x3fb8aa3b, v228
	v_exp_f32_e32 v228, v228
	s_nop 0
	v_add_f32_e32 v229, 1.0, v228
	v_div_scale_f32 v230, s[4:5], v229, v229, 2.0
	v_rcp_f32_e32 v231, v230
	v_div_scale_f32 v232, vcc, 2.0, v229, 2.0
	v_fma_f32 v131, -v230, v231, 1.0
	v_fmac_f32_e32 v231, v131, v231
	v_mul_f32_e32 v233, v232, v231
	v_fma_f32 v131, -v230, v233, v232
	v_fmac_f32_e32 v233, v131, v231
	v_fma_f32 v230, -v230, v233, v232
	v_div_fmas_f32 v230, v230, v231, v233
	v_div_fixup_f32 v133, v230, v229, 2.0
	v_sub_f32_e32 v133, 1.0, v133
	v_cvt_pk_bf16_f32 v133, v135, v133
	global_store_dword v[226:227], v133, off
	v_add_f32_e32 v228, v106, v106
	v_mul_f32_e32 v228, 0x3fb8aa3b, v228
	v_exp_f32_e32 v228, v228
	s_nop 0
	v_add_f32_e32 v229, 1.0, v228
	v_div_scale_f32 v230, s[4:5], v229, v229, 2.0
	v_rcp_f32_e32 v231, v230
	v_div_scale_f32 v232, vcc, 2.0, v229, 2.0
	v_fma_f32 v131, -v230, v231, 1.0
	v_fmac_f32_e32 v231, v131, v231
	v_mul_f32_e32 v233, v232, v231
	v_fma_f32 v131, -v230, v233, v232
	v_fmac_f32_e32 v233, v131, v231
	v_fma_f32 v230, -v230, v233, v232
	v_div_fmas_f32 v230, v230, v231, v233
	v_div_fixup_f32 v135, v230, v229, 2.0
	v_sub_f32_e32 v135, 1.0, v135
	v_add_f32_e32 v228, v110, v110
	v_mul_f32_e32 v228, 0x3fb8aa3b, v228
	v_exp_f32_e32 v228, v228
	s_nop 0
	v_add_f32_e32 v229, 1.0, v228
	v_div_scale_f32 v230, s[4:5], v229, v229, 2.0
	v_rcp_f32_e32 v231, v230
	v_div_scale_f32 v232, vcc, 2.0, v229, 2.0
	v_fma_f32 v131, -v230, v231, 1.0
	v_fmac_f32_e32 v231, v131, v231
	v_mul_f32_e32 v233, v232, v231
	v_fma_f32 v131, -v230, v233, v232
	v_fmac_f32_e32 v233, v131, v231
	v_fma_f32 v230, -v230, v233, v232
	v_div_fmas_f32 v230, v230, v231, v233
	v_div_fixup_f32 v133, v230, v229, 2.0
	v_sub_f32_e32 v133, 1.0, v133
	v_cvt_pk_bf16_f32 v133, v135, v133
	global_store_dword v[226:227], v133, off offset:64
	s_mov_b64 s[4:5], 0x300
	v_lshl_add_u64 v[226:227], v[226:227], 0, s[4:5]
	v_add_f32_e32 v228, v99, v99
	v_mul_f32_e32 v228, 0x3fb8aa3b, v228
	v_exp_f32_e32 v228, v228
	s_nop 0
	v_add_f32_e32 v229, 1.0, v228
	v_div_scale_f32 v230, s[4:5], v229, v229, 2.0
	v_rcp_f32_e32 v231, v230
	v_div_scale_f32 v232, vcc, 2.0, v229, 2.0
	v_fma_f32 v131, -v230, v231, 1.0
	v_fmac_f32_e32 v231, v131, v231
	v_mul_f32_e32 v233, v232, v231
	v_fma_f32 v131, -v230, v233, v232
	v_fmac_f32_e32 v233, v131, v231
	v_fma_f32 v230, -v230, v233, v232
	v_div_fmas_f32 v230, v230, v231, v233
	v_div_fixup_f32 v135, v230, v229, 2.0
	v_sub_f32_e32 v135, 1.0, v135
	v_add_f32_e32 v228, v103, v103
	v_mul_f32_e32 v228, 0x3fb8aa3b, v228
	v_exp_f32_e32 v228, v228
	s_nop 0
	v_add_f32_e32 v229, 1.0, v228
	v_div_scale_f32 v230, s[4:5], v229, v229, 2.0
	v_rcp_f32_e32 v231, v230
	v_div_scale_f32 v232, vcc, 2.0, v229, 2.0
	v_fma_f32 v131, -v230, v231, 1.0
	v_fmac_f32_e32 v231, v131, v231
	v_mul_f32_e32 v233, v232, v231
	v_fma_f32 v131, -v230, v233, v232
	v_fmac_f32_e32 v233, v131, v231
	v_fma_f32 v230, -v230, v233, v232
	v_div_fmas_f32 v230, v230, v231, v233
	v_div_fixup_f32 v133, v230, v229, 2.0
	v_sub_f32_e32 v133, 1.0, v133
	v_cvt_pk_bf16_f32 v133, v135, v133
	global_store_dword v[226:227], v133, off
	v_add_f32_e32 v228, v107, v107
	v_mul_f32_e32 v228, 0x3fb8aa3b, v228
	v_exp_f32_e32 v228, v228
	s_nop 0
	v_add_f32_e32 v229, 1.0, v228
	v_div_scale_f32 v230, s[4:5], v229, v229, 2.0
	v_rcp_f32_e32 v231, v230
	v_div_scale_f32 v232, vcc, 2.0, v229, 2.0
	v_fma_f32 v131, -v230, v231, 1.0
	v_fmac_f32_e32 v231, v131, v231
	v_mul_f32_e32 v233, v232, v231
	v_fma_f32 v131, -v230, v233, v232
	v_fmac_f32_e32 v233, v131, v231
	v_fma_f32 v230, -v230, v233, v232
	v_div_fmas_f32 v230, v230, v231, v233
	v_div_fixup_f32 v135, v230, v229, 2.0
	v_sub_f32_e32 v135, 1.0, v135
	v_add_f32_e32 v228, v111, v111
	v_mul_f32_e32 v228, 0x3fb8aa3b, v228
	v_exp_f32_e32 v228, v228
	s_nop 0
	v_add_f32_e32 v229, 1.0, v228
	v_div_scale_f32 v230, s[4:5], v229, v229, 2.0
	v_rcp_f32_e32 v231, v230
	v_div_scale_f32 v232, vcc, 2.0, v229, 2.0
	v_fma_f32 v131, -v230, v231, 1.0
	v_fmac_f32_e32 v231, v131, v231
	v_mul_f32_e32 v233, v232, v231
	v_fma_f32 v131, -v230, v233, v232
	v_fmac_f32_e32 v233, v131, v231
	v_fma_f32 v230, -v230, v233, v232
	v_div_fmas_f32 v230, v230, v231, v233
	v_div_fixup_f32 v133, v230, v229, 2.0
	v_sub_f32_e32 v133, 1.0, v133
	v_cvt_pk_bf16_f32 v133, v135, v133
	global_store_dword v[226:227], v133, off offset:64
	s_mov_b64 s[4:5], 0x2700
	v_lshl_add_u64 v[226:227], v[226:227], 0, s[4:5]
	v_add_f32_e32 v228, v112, v112
	v_mul_f32_e32 v228, 0x3fb8aa3b, v228
	v_exp_f32_e32 v228, v228
	s_nop 0
	v_add_f32_e32 v229, 1.0, v228
	v_div_scale_f32 v230, s[4:5], v229, v229, 2.0
	v_rcp_f32_e32 v231, v230
	v_div_scale_f32 v232, vcc, 2.0, v229, 2.0
	v_fma_f32 v131, -v230, v231, 1.0
	v_fmac_f32_e32 v231, v131, v231
	v_mul_f32_e32 v233, v232, v231
	v_fma_f32 v131, -v230, v233, v232
	v_fmac_f32_e32 v233, v131, v231
	v_fma_f32 v230, -v230, v233, v232
	v_div_fmas_f32 v230, v230, v231, v233
	v_div_fixup_f32 v135, v230, v229, 2.0
	v_sub_f32_e32 v135, 1.0, v135
	v_add_f32_e32 v228, v116, v116
	v_mul_f32_e32 v228, 0x3fb8aa3b, v228
	v_exp_f32_e32 v228, v228
	s_nop 0
	v_add_f32_e32 v229, 1.0, v228
	v_div_scale_f32 v230, s[4:5], v229, v229, 2.0
	v_rcp_f32_e32 v231, v230
	v_div_scale_f32 v232, vcc, 2.0, v229, 2.0
	v_fma_f32 v131, -v230, v231, 1.0
	v_fmac_f32_e32 v231, v131, v231
	v_mul_f32_e32 v233, v232, v231
	v_fma_f32 v131, -v230, v233, v232
	v_fmac_f32_e32 v233, v131, v231
	v_fma_f32 v230, -v230, v233, v232
	v_div_fmas_f32 v230, v230, v231, v233
	v_div_fixup_f32 v133, v230, v229, 2.0
	v_sub_f32_e32 v133, 1.0, v133
	v_cvt_pk_bf16_f32 v133, v135, v133
	global_store_dword v[226:227], v133, off
	v_add_f32_e32 v228, v120, v120
	v_mul_f32_e32 v228, 0x3fb8aa3b, v228
	v_exp_f32_e32 v228, v228
	s_nop 0
	v_add_f32_e32 v229, 1.0, v228
	v_div_scale_f32 v230, s[4:5], v229, v229, 2.0
	v_rcp_f32_e32 v231, v230
	v_div_scale_f32 v232, vcc, 2.0, v229, 2.0
	v_fma_f32 v131, -v230, v231, 1.0
	v_fmac_f32_e32 v231, v131, v231
	v_mul_f32_e32 v233, v232, v231
	v_fma_f32 v131, -v230, v233, v232
	v_fmac_f32_e32 v233, v131, v231
	v_fma_f32 v230, -v230, v233, v232
	v_div_fmas_f32 v230, v230, v231, v233
	v_div_fixup_f32 v135, v230, v229, 2.0
	v_sub_f32_e32 v135, 1.0, v135
	v_add_f32_e32 v228, v124, v124
	v_mul_f32_e32 v228, 0x3fb8aa3b, v228
	v_exp_f32_e32 v228, v228
	s_nop 0
	v_add_f32_e32 v229, 1.0, v228
	v_div_scale_f32 v230, s[4:5], v229, v229, 2.0
	v_rcp_f32_e32 v231, v230
	v_div_scale_f32 v232, vcc, 2.0, v229, 2.0
	v_fma_f32 v131, -v230, v231, 1.0
	v_fmac_f32_e32 v231, v131, v231
	v_mul_f32_e32 v233, v232, v231
	v_fma_f32 v131, -v230, v233, v232
	v_fmac_f32_e32 v233, v131, v231
	v_fma_f32 v230, -v230, v233, v232
	v_div_fmas_f32 v230, v230, v231, v233
	v_div_fixup_f32 v133, v230, v229, 2.0
	v_sub_f32_e32 v133, 1.0, v133
	v_cvt_pk_bf16_f32 v133, v135, v133
	global_store_dword v[226:227], v133, off offset:64
	s_mov_b64 s[4:5], 0x300
	v_lshl_add_u64 v[226:227], v[226:227], 0, s[4:5]
	v_add_f32_e32 v228, v113, v113
	v_mul_f32_e32 v228, 0x3fb8aa3b, v228
	v_exp_f32_e32 v228, v228
	s_nop 0
	v_add_f32_e32 v229, 1.0, v228
	v_div_scale_f32 v230, s[4:5], v229, v229, 2.0
	v_rcp_f32_e32 v231, v230
	v_div_scale_f32 v232, vcc, 2.0, v229, 2.0
	v_fma_f32 v131, -v230, v231, 1.0
	v_fmac_f32_e32 v231, v131, v231
	v_mul_f32_e32 v233, v232, v231
	v_fma_f32 v131, -v230, v233, v232
	v_fmac_f32_e32 v233, v131, v231
	v_fma_f32 v230, -v230, v233, v232
	v_div_fmas_f32 v230, v230, v231, v233
	v_div_fixup_f32 v135, v230, v229, 2.0
	v_sub_f32_e32 v135, 1.0, v135
	v_add_f32_e32 v228, v117, v117
	v_mul_f32_e32 v228, 0x3fb8aa3b, v228
	v_exp_f32_e32 v228, v228
	s_nop 0
	v_add_f32_e32 v229, 1.0, v228
	v_div_scale_f32 v230, s[4:5], v229, v229, 2.0
	v_rcp_f32_e32 v231, v230
	v_div_scale_f32 v232, vcc, 2.0, v229, 2.0
	v_fma_f32 v131, -v230, v231, 1.0
	v_fmac_f32_e32 v231, v131, v231
	v_mul_f32_e32 v233, v232, v231
	v_fma_f32 v131, -v230, v233, v232
	v_fmac_f32_e32 v233, v131, v231
	v_fma_f32 v230, -v230, v233, v232
	v_div_fmas_f32 v230, v230, v231, v233
	v_div_fixup_f32 v133, v230, v229, 2.0
	v_sub_f32_e32 v133, 1.0, v133
	v_cvt_pk_bf16_f32 v133, v135, v133
	global_store_dword v[226:227], v133, off
	v_add_f32_e32 v228, v121, v121
	v_mul_f32_e32 v228, 0x3fb8aa3b, v228
	v_exp_f32_e32 v228, v228
	s_nop 0
	v_add_f32_e32 v229, 1.0, v228
	v_div_scale_f32 v230, s[4:5], v229, v229, 2.0
	v_rcp_f32_e32 v231, v230
	v_div_scale_f32 v232, vcc, 2.0, v229, 2.0
	v_fma_f32 v131, -v230, v231, 1.0
	v_fmac_f32_e32 v231, v131, v231
	v_mul_f32_e32 v233, v232, v231
	v_fma_f32 v131, -v230, v233, v232
	v_fmac_f32_e32 v233, v131, v231
	v_fma_f32 v230, -v230, v233, v232
	v_div_fmas_f32 v230, v230, v231, v233
	v_div_fixup_f32 v135, v230, v229, 2.0
	v_sub_f32_e32 v135, 1.0, v135
	v_add_f32_e32 v228, v125, v125
	v_mul_f32_e32 v228, 0x3fb8aa3b, v228
	v_exp_f32_e32 v228, v228
	s_nop 0
	v_add_f32_e32 v229, 1.0, v228
	v_div_scale_f32 v230, s[4:5], v229, v229, 2.0
	v_rcp_f32_e32 v231, v230
	v_div_scale_f32 v232, vcc, 2.0, v229, 2.0
	v_fma_f32 v131, -v230, v231, 1.0
	v_fmac_f32_e32 v231, v131, v231
	v_mul_f32_e32 v233, v232, v231
	v_fma_f32 v131, -v230, v233, v232
	v_fmac_f32_e32 v233, v131, v231
	v_fma_f32 v230, -v230, v233, v232
	v_div_fmas_f32 v230, v230, v231, v233
	v_div_fixup_f32 v133, v230, v229, 2.0
	v_sub_f32_e32 v133, 1.0, v133
	v_cvt_pk_bf16_f32 v133, v135, v133
	global_store_dword v[226:227], v133, off offset:64
	s_mov_b64 s[4:5], 0x300
	v_lshl_add_u64 v[226:227], v[226:227], 0, s[4:5]
	v_add_f32_e32 v228, v114, v114
	v_mul_f32_e32 v228, 0x3fb8aa3b, v228
	v_exp_f32_e32 v228, v228
	s_nop 0
	v_add_f32_e32 v229, 1.0, v228
	v_div_scale_f32 v230, s[4:5], v229, v229, 2.0
	v_rcp_f32_e32 v231, v230
	v_div_scale_f32 v232, vcc, 2.0, v229, 2.0
	v_fma_f32 v131, -v230, v231, 1.0
	v_fmac_f32_e32 v231, v131, v231
	v_mul_f32_e32 v233, v232, v231
	v_fma_f32 v131, -v230, v233, v232
	v_fmac_f32_e32 v233, v131, v231
	v_fma_f32 v230, -v230, v233, v232
	v_div_fmas_f32 v230, v230, v231, v233
	v_div_fixup_f32 v135, v230, v229, 2.0
	v_sub_f32_e32 v135, 1.0, v135
	v_add_f32_e32 v228, v118, v118
	v_mul_f32_e32 v228, 0x3fb8aa3b, v228
	v_exp_f32_e32 v228, v228
	s_nop 0
	v_add_f32_e32 v229, 1.0, v228
	v_div_scale_f32 v230, s[4:5], v229, v229, 2.0
	v_rcp_f32_e32 v231, v230
	v_div_scale_f32 v232, vcc, 2.0, v229, 2.0
	v_fma_f32 v131, -v230, v231, 1.0
	v_fmac_f32_e32 v231, v131, v231
	v_mul_f32_e32 v233, v232, v231
	v_fma_f32 v131, -v230, v233, v232
	v_fmac_f32_e32 v233, v131, v231
	v_fma_f32 v230, -v230, v233, v232
	v_div_fmas_f32 v230, v230, v231, v233
	v_div_fixup_f32 v133, v230, v229, 2.0
	v_sub_f32_e32 v133, 1.0, v133
	v_cvt_pk_bf16_f32 v133, v135, v133
	global_store_dword v[226:227], v133, off
	v_add_f32_e32 v228, v122, v122
	v_mul_f32_e32 v228, 0x3fb8aa3b, v228
	v_exp_f32_e32 v228, v228
	s_nop 0
	v_add_f32_e32 v229, 1.0, v228
	v_div_scale_f32 v230, s[4:5], v229, v229, 2.0
	v_rcp_f32_e32 v231, v230
	v_div_scale_f32 v232, vcc, 2.0, v229, 2.0
	v_fma_f32 v131, -v230, v231, 1.0
	v_fmac_f32_e32 v231, v131, v231
	v_mul_f32_e32 v233, v232, v231
	v_fma_f32 v131, -v230, v233, v232
	v_fmac_f32_e32 v233, v131, v231
	v_fma_f32 v230, -v230, v233, v232
	v_div_fmas_f32 v230, v230, v231, v233
	v_div_fixup_f32 v135, v230, v229, 2.0
	v_sub_f32_e32 v135, 1.0, v135
	v_add_f32_e32 v228, v126, v126
	v_mul_f32_e32 v228, 0x3fb8aa3b, v228
	v_exp_f32_e32 v228, v228
	s_nop 0
	v_add_f32_e32 v229, 1.0, v228
	v_div_scale_f32 v230, s[4:5], v229, v229, 2.0
	v_rcp_f32_e32 v231, v230
	v_div_scale_f32 v232, vcc, 2.0, v229, 2.0
	v_fma_f32 v131, -v230, v231, 1.0
	v_fmac_f32_e32 v231, v131, v231
	v_mul_f32_e32 v233, v232, v231
	v_fma_f32 v131, -v230, v233, v232
	v_fmac_f32_e32 v233, v131, v231
	v_fma_f32 v230, -v230, v233, v232
	v_div_fmas_f32 v230, v230, v231, v233
	v_div_fixup_f32 v133, v230, v229, 2.0
	v_sub_f32_e32 v133, 1.0, v133
	v_cvt_pk_bf16_f32 v133, v135, v133
	global_store_dword v[226:227], v133, off offset:64
	s_mov_b64 s[4:5], 0x300
	v_lshl_add_u64 v[226:227], v[226:227], 0, s[4:5]
	v_add_f32_e32 v228, v115, v115
	v_mul_f32_e32 v228, 0x3fb8aa3b, v228
	v_exp_f32_e32 v228, v228
	s_nop 0
	v_add_f32_e32 v229, 1.0, v228
	v_div_scale_f32 v230, s[4:5], v229, v229, 2.0
	v_rcp_f32_e32 v231, v230
	v_div_scale_f32 v232, vcc, 2.0, v229, 2.0
	v_fma_f32 v131, -v230, v231, 1.0
	v_fmac_f32_e32 v231, v131, v231
	v_mul_f32_e32 v233, v232, v231
	v_fma_f32 v131, -v230, v233, v232
	v_fmac_f32_e32 v233, v131, v231
	v_fma_f32 v230, -v230, v233, v232
	v_div_fmas_f32 v230, v230, v231, v233
	v_div_fixup_f32 v135, v230, v229, 2.0
	v_sub_f32_e32 v135, 1.0, v135
	v_add_f32_e32 v228, v119, v119
	v_mul_f32_e32 v228, 0x3fb8aa3b, v228
	v_exp_f32_e32 v228, v228
	s_nop 0
	v_add_f32_e32 v229, 1.0, v228
	v_div_scale_f32 v230, s[4:5], v229, v229, 2.0
	v_rcp_f32_e32 v231, v230
	v_div_scale_f32 v232, vcc, 2.0, v229, 2.0
	v_fma_f32 v131, -v230, v231, 1.0
	v_fmac_f32_e32 v231, v131, v231
	v_mul_f32_e32 v233, v232, v231
	v_fma_f32 v131, -v230, v233, v232
	v_fmac_f32_e32 v233, v131, v231
	v_fma_f32 v230, -v230, v233, v232
	v_div_fmas_f32 v230, v230, v231, v233
	v_div_fixup_f32 v133, v230, v229, 2.0
	v_sub_f32_e32 v133, 1.0, v133
	v_cvt_pk_bf16_f32 v133, v135, v133
	global_store_dword v[226:227], v133, off
	v_add_f32_e32 v228, v123, v123
	v_mul_f32_e32 v228, 0x3fb8aa3b, v228
	v_exp_f32_e32 v228, v228
	s_nop 0
	v_add_f32_e32 v229, 1.0, v228
	v_div_scale_f32 v230, s[4:5], v229, v229, 2.0
	v_rcp_f32_e32 v231, v230
	v_div_scale_f32 v232, vcc, 2.0, v229, 2.0
	v_fma_f32 v131, -v230, v231, 1.0
	v_fmac_f32_e32 v231, v131, v231
	v_mul_f32_e32 v233, v232, v231
	v_fma_f32 v131, -v230, v233, v232
	v_fmac_f32_e32 v233, v131, v231
	v_fma_f32 v230, -v230, v233, v232
	v_div_fmas_f32 v230, v230, v231, v233
	v_div_fixup_f32 v135, v230, v229, 2.0
	v_sub_f32_e32 v135, 1.0, v135
	v_add_f32_e32 v228, v127, v127
	v_mul_f32_e32 v228, 0x3fb8aa3b, v228
	v_exp_f32_e32 v228, v228
	s_nop 0
	v_add_f32_e32 v229, 1.0, v228
	v_div_scale_f32 v230, s[4:5], v229, v229, 2.0
	v_rcp_f32_e32 v231, v230
	v_div_scale_f32 v232, vcc, 2.0, v229, 2.0
	v_fma_f32 v131, -v230, v231, 1.0
	v_fmac_f32_e32 v231, v131, v231
	v_mul_f32_e32 v233, v232, v231
	v_fma_f32 v131, -v230, v233, v232
	v_fmac_f32_e32 v233, v131, v231
	v_fma_f32 v230, -v230, v233, v232
	v_div_fmas_f32 v230, v230, v231, v233
	v_div_fixup_f32 v133, v230, v229, 2.0
	v_sub_f32_e32 v133, 1.0, v133
	v_cvt_pk_bf16_f32 v133, v135, v133
	global_store_dword v[226:227], v133, off offset:64
	s_branch .Lip_nolin
.Lip_lin1:
	s_cmp_lg_u32 s55, 1
	s_cbranch_scc1 .Lip_lin2
	v_mov_b32_e32 v226, s50
	v_mov_b32_e32 v227, s51
	v_add_co_u32_e32 v226, vcc, v226, v169
	s_nop 1
	v_addc_co_u32_e32 v227, vcc, 0, v227, vcc
	v_cvt_pk_bf16_f32 v133, v0, v4
	global_store_dword v[226:227], v133, off
	v_cvt_pk_bf16_f32 v133, v8, v12
	global_store_dword v[226:227], v133, off offset:64
	s_mov_b64 s[4:5], 0x300
	v_lshl_add_u64 v[226:227], v[226:227], 0, s[4:5]
	v_cvt_pk_bf16_f32 v133, v1, v5
	global_store_dword v[226:227], v133, off
	v_cvt_pk_bf16_f32 v133, v9, v13
	global_store_dword v[226:227], v133, off offset:64
	s_mov_b64 s[4:5], 0x300
	v_lshl_add_u64 v[226:227], v[226:227], 0, s[4:5]
	v_cvt_pk_bf16_f32 v133, v2, v6
	global_store_dword v[226:227], v133, off
	v_cvt_pk_bf16_f32 v133, v10, v14
	global_store_dword v[226:227], v133, off offset:64
	s_mov_b64 s[4:5], 0x300
	v_lshl_add_u64 v[226:227], v[226:227], 0, s[4:5]
	v_cvt_pk_bf16_f32 v133, v3, v7
	global_store_dword v[226:227], v133, off
	v_cvt_pk_bf16_f32 v133, v11, v15
	global_store_dword v[226:227], v133, off offset:64
	s_mov_b64 s[4:5], 0x2700
	v_lshl_add_u64 v[226:227], v[226:227], 0, s[4:5]
	v_cvt_pk_bf16_f32 v133, v16, v20
	global_store_dword v[226:227], v133, off
	v_cvt_pk_bf16_f32 v133, v24, v28
	global_store_dword v[226:227], v133, off offset:64
	s_mov_b64 s[4:5], 0x300
	v_lshl_add_u64 v[226:227], v[226:227], 0, s[4:5]
	v_cvt_pk_bf16_f32 v133, v17, v21
	global_store_dword v[226:227], v133, off
	v_cvt_pk_bf16_f32 v133, v25, v29
	global_store_dword v[226:227], v133, off offset:64
	s_mov_b64 s[4:5], 0x300
	v_lshl_add_u64 v[226:227], v[226:227], 0, s[4:5]
	v_cvt_pk_bf16_f32 v133, v18, v22
	global_store_dword v[226:227], v133, off
	v_cvt_pk_bf16_f32 v133, v26, v30
	global_store_dword v[226:227], v133, off offset:64
	s_mov_b64 s[4:5], 0x300
	v_lshl_add_u64 v[226:227], v[226:227], 0, s[4:5]
	v_cvt_pk_bf16_f32 v133, v19, v23
	global_store_dword v[226:227], v133, off
	v_cvt_pk_bf16_f32 v133, v27, v31
	global_store_dword v[226:227], v133, off offset:64
	s_mov_b64 s[4:5], 0x2700
	v_lshl_add_u64 v[226:227], v[226:227], 0, s[4:5]
	v_cvt_pk_bf16_f32 v133, v32, v36
	global_store_dword v[226:227], v133, off
	v_cvt_pk_bf16_f32 v133, v40, v44
	global_store_dword v[226:227], v133, off offset:64
	s_mov_b64 s[4:5], 0x300
	v_lshl_add_u64 v[226:227], v[226:227], 0, s[4:5]
	v_cvt_pk_bf16_f32 v133, v33, v37
	global_store_dword v[226:227], v133, off
	v_cvt_pk_bf16_f32 v133, v41, v45
	global_store_dword v[226:227], v133, off offset:64
	s_mov_b64 s[4:5], 0x300
	v_lshl_add_u64 v[226:227], v[226:227], 0, s[4:5]
	v_cvt_pk_bf16_f32 v133, v34, v38
	global_store_dword v[226:227], v133, off
	v_cvt_pk_bf16_f32 v133, v42, v46
	global_store_dword v[226:227], v133, off offset:64
	s_mov_b64 s[4:5], 0x300
	v_lshl_add_u64 v[226:227], v[226:227], 0, s[4:5]
	v_cvt_pk_bf16_f32 v133, v35, v39
	global_store_dword v[226:227], v133, off
	v_cvt_pk_bf16_f32 v133, v43, v47
	global_store_dword v[226:227], v133, off offset:64
	s_mov_b64 s[4:5], 0x2700
	v_lshl_add_u64 v[226:227], v[226:227], 0, s[4:5]
	v_cvt_pk_bf16_f32 v133, v48, v52
	global_store_dword v[226:227], v133, off
	v_cvt_pk_bf16_f32 v133, v56, v60
	global_store_dword v[226:227], v133, off offset:64
	s_mov_b64 s[4:5], 0x300
	v_lshl_add_u64 v[226:227], v[226:227], 0, s[4:5]
	v_cvt_pk_bf16_f32 v133, v49, v53
	global_store_dword v[226:227], v133, off
	v_cvt_pk_bf16_f32 v133, v57, v61
	global_store_dword v[226:227], v133, off offset:64
	s_mov_b64 s[4:5], 0x300
	v_lshl_add_u64 v[226:227], v[226:227], 0, s[4:5]
	v_cvt_pk_bf16_f32 v133, v50, v54
	global_store_dword v[226:227], v133, off
	v_cvt_pk_bf16_f32 v133, v58, v62
	global_store_dword v[226:227], v133, off offset:64
	s_mov_b64 s[4:5], 0x300
	v_lshl_add_u64 v[226:227], v[226:227], 0, s[4:5]
	v_cvt_pk_bf16_f32 v133, v51, v55
	global_store_dword v[226:227], v133, off
	v_cvt_pk_bf16_f32 v133, v59, v63
	global_store_dword v[226:227], v133, off offset:64
	s_mov_b64 s[4:5], 0x2700
	v_lshl_add_u64 v[226:227], v[226:227], 0, s[4:5]
	v_cvt_pk_bf16_f32 v133, v64, v68
	global_store_dword v[226:227], v133, off
	v_cvt_pk_bf16_f32 v133, v72, v76
	global_store_dword v[226:227], v133, off offset:64
	s_mov_b64 s[4:5], 0x300
	v_lshl_add_u64 v[226:227], v[226:227], 0, s[4:5]
	v_cvt_pk_bf16_f32 v133, v65, v69
	global_store_dword v[226:227], v133, off
	v_cvt_pk_bf16_f32 v133, v73, v77
	global_store_dword v[226:227], v133, off offset:64
	s_mov_b64 s[4:5], 0x300
	v_lshl_add_u64 v[226:227], v[226:227], 0, s[4:5]
	v_cvt_pk_bf16_f32 v133, v66, v70
	global_store_dword v[226:227], v133, off
	v_cvt_pk_bf16_f32 v133, v74, v78
	global_store_dword v[226:227], v133, off offset:64
	s_mov_b64 s[4:5], 0x300
	v_lshl_add_u64 v[226:227], v[226:227], 0, s[4:5]
	v_cvt_pk_bf16_f32 v133, v67, v71
	global_store_dword v[226:227], v133, off
	v_cvt_pk_bf16_f32 v133, v75, v79
	global_store_dword v[226:227], v133, off offset:64
	s_mov_b64 s[4:5], 0x2700
	v_lshl_add_u64 v[226:227], v[226:227], 0, s[4:5]
	v_cvt_pk_bf16_f32 v133, v80, v84
	global_store_dword v[226:227], v133, off
	v_cvt_pk_bf16_f32 v133, v88, v92
	global_store_dword v[226:227], v133, off offset:64
	s_mov_b64 s[4:5], 0x300
	v_lshl_add_u64 v[226:227], v[226:227], 0, s[4:5]
	v_cvt_pk_bf16_f32 v133, v81, v85
	global_store_dword v[226:227], v133, off
	v_cvt_pk_bf16_f32 v133, v89, v93
	global_store_dword v[226:227], v133, off offset:64
	s_mov_b64 s[4:5], 0x300
	v_lshl_add_u64 v[226:227], v[226:227], 0, s[4:5]
	v_cvt_pk_bf16_f32 v133, v82, v86
	global_store_dword v[226:227], v133, off
	v_cvt_pk_bf16_f32 v133, v90, v94
	global_store_dword v[226:227], v133, off offset:64
	s_mov_b64 s[4:5], 0x300
	v_lshl_add_u64 v[226:227], v[226:227], 0, s[4:5]
	v_cvt_pk_bf16_f32 v133, v83, v87
	global_store_dword v[226:227], v133, off
	v_cvt_pk_bf16_f32 v133, v91, v95
	global_store_dword v[226:227], v133, off offset:64
	s_mov_b64 s[4:5], 0x2700
	v_lshl_add_u64 v[226:227], v[226:227], 0, s[4:5]
	v_cvt_pk_bf16_f32 v133, v96, v100
	global_store_dword v[226:227], v133, off
	v_cvt_pk_bf16_f32 v133, v104, v108
	global_store_dword v[226:227], v133, off offset:64
	s_mov_b64 s[4:5], 0x300
	v_lshl_add_u64 v[226:227], v[226:227], 0, s[4:5]
	v_cvt_pk_bf16_f32 v133, v97, v101
	global_store_dword v[226:227], v133, off
	v_cvt_pk_bf16_f32 v133, v105, v109
	global_store_dword v[226:227], v133, off offset:64
	s_mov_b64 s[4:5], 0x300
	v_lshl_add_u64 v[226:227], v[226:227], 0, s[4:5]
	v_cvt_pk_bf16_f32 v133, v98, v102
	global_store_dword v[226:227], v133, off
	v_cvt_pk_bf16_f32 v133, v106, v110
	global_store_dword v[226:227], v133, off offset:64
	s_mov_b64 s[4:5], 0x300
	v_lshl_add_u64 v[226:227], v[226:227], 0, s[4:5]
	v_cvt_pk_bf16_f32 v133, v99, v103
	global_store_dword v[226:227], v133, off
	v_cvt_pk_bf16_f32 v133, v107, v111
	global_store_dword v[226:227], v133, off offset:64
	s_mov_b64 s[4:5], 0x2700
	v_lshl_add_u64 v[226:227], v[226:227], 0, s[4:5]
	v_cvt_pk_bf16_f32 v133, v112, v116
	global_store_dword v[226:227], v133, off
	v_cvt_pk_bf16_f32 v133, v120, v124
	global_store_dword v[226:227], v133, off offset:64
	s_mov_b64 s[4:5], 0x300
	v_lshl_add_u64 v[226:227], v[226:227], 0, s[4:5]
	v_cvt_pk_bf16_f32 v133, v113, v117
	global_store_dword v[226:227], v133, off
	v_cvt_pk_bf16_f32 v133, v121, v125
	global_store_dword v[226:227], v133, off offset:64
	s_mov_b64 s[4:5], 0x300
	v_lshl_add_u64 v[226:227], v[226:227], 0, s[4:5]
	v_cvt_pk_bf16_f32 v133, v114, v118
	global_store_dword v[226:227], v133, off
	v_cvt_pk_bf16_f32 v133, v122, v126
	global_store_dword v[226:227], v133, off offset:64
	s_mov_b64 s[4:5], 0x300
	v_lshl_add_u64 v[226:227], v[226:227], 0, s[4:5]
	v_cvt_pk_bf16_f32 v133, v115, v119
	global_store_dword v[226:227], v133, off
	v_cvt_pk_bf16_f32 v133, v123, v127
	global_store_dword v[226:227], v133, off offset:64
	s_branch .Lip_nolin

.Lip_nolin:
	s_cmp_ge_u32 s54, 1296
	s_cbranch_scc1 .Lip_done
	s_lshr_b32 s55, s54, 4
	s_mul_hi_u32 s55, s55, 0x55555556
	s_mul_i32 s53, s55, 48
	s_sub_u32 s53, s54, s53
	v_readlane_b32 s4, v235, 34
	v_readlane_b32 s5, v235, 35
	s_lshl_b32 s56, s53, 8
	s_or_b32 s56, s56, s55
	s_branch .Lip_tile
